# MLA: both barrier points two MFMAs earlier (waves 0-3 behind their 2nd PV MFMA, waves 4-7 behind the 6th QK MFMA)
# baseline (speedup 1.0000x reference)
; __device__ __forceinline__ void finishSM9(f32x16& p0, f32x16& p1, float alpha, float& l_reg, v8i32& p8) {
; #pragma unroll
;   for (int r = 0; r < 16; ++r) { p0[r] = __builtin_amdgcn_exp2f(p0[r]); p1[r] = __builtin_amdgcn_exp2f(p1[r]); }
;   float ps = 0;
; #pragma unroll
;   for (int r = 0; r < 16; ++r) ps += p0[r];
; #pragma unroll
;   for (int r = 0; r < 16; ++r) ps += p1[r];
;   { auto rr = __builtin_amdgcn_permlane32_swap(__float_as_uint(ps), __float_as_uint(ps), false, false);
;     ps = __uint_as_float(rr[0]) + __uint_as_float(rr[1]); }
;   l_reg = l_reg * alpha + ps;
; #pragma unroll
;   for (int g = 0; g < 4; ++g) {
;     int w = __builtin_amdgcn_cvt_pk_fp8_f32(p0[4 * g], p0[4 * g + 1], 0, false); p8[g] = __builtin_amdgcn_cvt_pk_fp8_f32(p0[4 * g + 2], p0[4 * g + 3], w, true);
;     int u = __builtin_amdgcn_cvt_pk_fp8_f32(p1[4 * g], p1[4 * g + 1], 0, false); p8[4 + g] = __builtin_amdgcn_cvt_pk_fp8_f32(p1[4 * g + 2], p1[4 * g + 3], u, true); }
; }
; __device__ __forceinline__ void pv8(f32x16* o, const char* Vt, const v8i32 p8, int r32, int hi) {
;   const int sw = (r32 >> 2) & 3, a0 = r32 * 64 + (((hi * 2) ^ sw) << 4), a1 = r32 * 64 + (((hi * 2 + 1) ^ sw) << 4);
; #pragma unroll
;   for (int d0 = 0; d0 < 4; ++d0) {
;     const v8i32 vf = cat8(*reinterpret_cast<const v4i32*>(Vt + d0 * 2048 + a0), *reinterpret_cast<const v4i32*>(Vt + d0 * 2048 + a1));
;     o[d0] = __builtin_amdgcn_mfma_scale_f32_32x32x64_f8f6f4(p8, vf, o[d0], 0, 0, 0, 127, 0, 127); }
; }
; __device__ __forceinline__ void qkt9(f32x16& p0, f32x16& p1, const char* Kn, const char* Kr, const v8i32* qf, const float init, int r32, int hi) {
; #pragma unroll
;   for (int r = 0; r < 16; ++r) { p0[r] = init; p1[r] = init; }
; #pragma unroll
;   for (int s = 0; s < 2; ++s) { const int c0 = s * 4 + hi * 2;
;     const v8i32 a0 = cat8(*reinterpret_cast<const v4i32*>(Kn + KN8SW(r32, c0)), *reinterpret_cast<const v4i32*>(Kn + KN8SW(r32, c0 + 1)));
;     const v8i32 a1 = cat8(*reinterpret_cast<const v4i32*>(Kn + 4096 + KN8SW(r32, c0)), *reinterpret_cast<const v4i32*>(Kn + 4096 + KN8SW(r32, c0 + 1)));
;     p0 = __builtin_amdgcn_mfma_scale_f32_32x32x64_f8f6f4(a0, qf[s], p0, 0, 0, 0, 127, 0, 124);
;     p1 = __builtin_amdgcn_mfma_scale_f32_32x32x64_f8f6f4(a1, qf[s], p1, 0, 0, 0, 127, 0, 124); }
;   { const int c0 = hi * 2;
.LBB0_1321:
	ds_read_b128 v[114:117], v215 offset:24576
	ds_read_b128 v[118:121], v216 offset:24576
	ds_read_b128 v[222:225], v215 offset:28672
	ds_read_b128 v[226:229], v216 offset:28672
	global_load_dwordx4 v[158:161], v176, s[18:19]
	global_load_dwordx4 v[162:165], v178, s[16:17]
	global_load_dwordx4 v[154:157], v[180:181], off
	v_add_u32_e32 v176, 0x2000, v176
	v_add_u32_e32 v178, 0x20000, v178
	s_mov_b64 s[20:21], 0x1000
	v_lshl_add_u64 v[180:181], v[180:181], 0, s[20:21]
	v_exp_f32_e32 v0, v82
	v_exp_f32_e32 v177, v83
	v_exp_f32_e32 v179, v84
	v_exp_f32_e32 v254, v85
	v_add_f32_e32 v219, v0, v177
	v_cvt_pk_fp8_f32 v246, v0, v177
	v_add_f32_e32 v219, v179, v219
	v_add_f32_e32 v219, v254, v219
	v_cvt_pk_fp8_f32 v246, v179, v254 op_sel:[0,0,1]
	s_waitcnt lgkmcnt(2)
	v_mfma_scale_f32_32x32x64_f8f6f4 v[114:129], v[114:121], v[146:153], v[230:245], v194, v193 op_sel_hi:[0,0,0]
	v_exp_f32_e32 v0, v86
	v_exp_f32_e32 v177, v87
	v_exp_f32_e32 v179, v88
	v_exp_f32_e32 v254, v89
	v_add_f32_e32 v219, v0, v219
	v_add_f32_e32 v219, v177, v219
	v_cvt_pk_fp8_f32 v247, v0, v177
	v_add_f32_e32 v219, v179, v219
	v_add_f32_e32 v219, v254, v219
	v_cvt_pk_fp8_f32 v247, v179, v254 op_sel:[0,0,1]
	ds_read_b128 v[82:85], v213 offset:24576
	ds_read_b128 v[86:89], v214 offset:24576
	s_waitcnt lgkmcnt(2)
	v_mfma_scale_f32_32x32x64_f8f6f4 v[98:113], v[222:229], v[146:153], v[230:245], v194, v193 op_sel_hi:[0,0,0]
	ds_read_b128 v[222:225], v213 offset:28672
	ds_read_b128 v[226:229], v214 offset:28672
	v_exp_f32_e32 v0, v90
	v_exp_f32_e32 v177, v91
	v_exp_f32_e32 v179, v92
	v_exp_f32_e32 v254, v93
	v_add_f32_e32 v219, v0, v219
	v_add_f32_e32 v219, v177, v219
	v_cvt_pk_fp8_f32 v248, v0, v177
	v_add_f32_e32 v219, v179, v219
	v_add_f32_e32 v219, v254, v219
	v_cvt_pk_fp8_f32 v248, v179, v254 op_sel:[0,0,1]
	v_exp_f32_e32 v0, v94
	v_exp_f32_e32 v177, v95
	v_exp_f32_e32 v179, v96
	v_exp_f32_e32 v254, v97
	v_add_f32_e32 v219, v0, v219
	v_add_f32_e32 v219, v177, v219
	v_cvt_pk_fp8_f32 v249, v0, v177
	v_add_f32_e32 v219, v179, v219
	v_add_f32_e32 v219, v254, v219
	v_cvt_pk_fp8_f32 v249, v179, v254 op_sel:[0,0,1]
	ds_read_b128 v[90:93], v185 offset:36864
	ds_read_b128 v[94:97], v186 offset:36864
	s_waitcnt lgkmcnt(4)
	v_mfma_scale_f32_32x32x64_f8f6f4 v[114:129], v[82:89], v[138:145], v[114:129], v194, v193 op_sel_hi:[0,0,0]
	v_exp_f32_e32 v0, v66
	v_exp_f32_e32 v177, v67
	v_exp_f32_e32 v179, v68
	v_exp_f32_e32 v254, v69
	v_add_f32_e32 v219, v0, v219
	v_add_f32_e32 v219, v177, v219
	v_cvt_pk_fp8_f32 v250, v0, v177
	v_add_f32_e32 v219, v179, v219
	v_add_f32_e32 v219, v254, v219
	v_cvt_pk_fp8_f32 v250, v179, v254 op_sel:[0,0,1]
	s_waitcnt lgkmcnt(2)
	v_mfma_scale_f32_32x32x64_f8f6f4 v[98:113], v[222:229], v[138:145], v[98:113], v194, v193 op_sel_hi:[0,0,0]
	ds_read_b128 v[222:225], v185 offset:38912
	ds_read_b128 v[226:229], v186 offset:38912
	v_exp_f32_e32 v0, v70
	v_exp_f32_e32 v177, v71
	v_exp_f32_e32 v179, v72
	v_exp_f32_e32 v254, v73
	v_add_f32_e32 v219, v0, v219
	v_add_f32_e32 v219, v177, v219
	v_cvt_pk_fp8_f32 v251, v0, v177
	v_add_f32_e32 v219, v179, v219
	v_add_f32_e32 v219, v254, v219
	v_cvt_pk_fp8_f32 v251, v179, v254 op_sel:[0,0,1]
	v_exp_f32_e32 v0, v74
	v_exp_f32_e32 v177, v75
	v_exp_f32_e32 v179, v76
	v_exp_f32_e32 v254, v77
	v_add_f32_e32 v219, v0, v219
	v_add_f32_e32 v219, v177, v219
	v_cvt_pk_fp8_f32 v252, v0, v177
	v_add_f32_e32 v219, v179, v219
	v_add_f32_e32 v219, v254, v219
	v_cvt_pk_fp8_f32 v252, v179, v254 op_sel:[0,0,1]
	s_waitcnt lgkmcnt(2)
	v_mfma_scale_f32_32x32x64_f8f6f4 v[114:129], v[90:97], v[130:137], v[114:129], v194, v193 op_sel_hi:[0,0,0]
	v_exp_f32_e32 v0, v78
	v_exp_f32_e32 v177, v79
	v_exp_f32_e32 v179, v80
	v_exp_f32_e32 v254, v81
	v_add_f32_e32 v219, v0, v219
	v_add_f32_e32 v219, v177, v219
	v_cvt_pk_fp8_f32 v253, v0, v177
	v_add_f32_e32 v219, v179, v219
	v_add_f32_e32 v219, v254, v219
	v_cvt_pk_fp8_f32 v253, v179, v254 op_sel:[0,0,1]
	ds_read_b128 v[90:93], v185 offset:0
	ds_read_b128 v[94:97], v186 offset:0
	ds_read_b128 v[82:85], v185 offset:2048
	ds_read_b128 v[86:89], v186 offset:2048
	ds_read_b128 v[74:77], v185 offset:4096
	ds_read_b128 v[78:81], v186 offset:4096
	ds_read_b128 v[66:69], v185 offset:6144
	ds_read_b128 v[70:73], v186 offset:6144
	s_waitcnt lgkmcnt(8)
	v_mfma_scale_f32_32x32x64_f8f6f4 v[98:113], v[222:229], v[130:137], v[98:113], v194, v193 op_sel_hi:[0,0,0]
	v_mov_b32_e32 v0, v219
	s_nop 1
	v_permlane32_swap_b32_e32 v219, v0
	v_add_f32_e32 v219, v219, v0
	v_fma_f32 v209, v209, v218, v219
	v_max_f32_e32 v177, v114, v115
	v_max3_f32 v177, v177, v116, v117
	v_max3_f32 v177, v177, v118, v119
	v_max3_f32 v177, v177, v120, v121
	v_max3_f32 v177, v177, v122, v123
	v_max3_f32 v177, v177, v124, v125
	v_max3_f32 v177, v177, v126, v127
	v_max3_f32 v177, v177, v128, v129
	s_waitcnt lgkmcnt(6)
	v_mfma_scale_f32_32x32x64_f8f6f4 v[50:65], v[246:253], v[90:97], v[50:65], v194, v194 op_sel_hi:[0,0,0]
	s_waitcnt vmcnt(0)
	ds_write_b128 v210, v[158:161] offset:43008
	ds_write_b128 v211, v[162:165] offset:51200
	ds_write_b128 v212, v[154:157] offset:59392
	s_waitcnt lgkmcnt(7)
	v_mfma_scale_f32_32x32x64_f8f6f4 v[34:49], v[246:253], v[82:89], v[34:49], v194, v194 op_sel_hi:[0,0,0]
	s_waitcnt lgkmcnt(0)
	s_barrier
	s_waitcnt lgkmcnt(2)
	v_mfma_scale_f32_32x32x64_f8f6f4 v[18:33], v[246:253], v[74:81], v[18:33], v194, v194 op_sel_hi:[0,0,0]
	s_waitcnt lgkmcnt(0)
	v_mfma_scale_f32_32x32x64_f8f6f4 v[2:17], v[246:253], v[66:73], v[2:17], v194, v194 op_sel_hi:[0,0,0]
	v_max_f32_e32 v0, v98, v99
	v_max3_f32 v0, v0, v100, v101
	v_max3_f32 v0, v0, v102, v103
	v_max3_f32 v0, v0, v104, v105
	v_max3_f32 v0, v0, v106, v107
	v_max3_f32 v0, v0, v108, v109
	v_max3_f32 v0, v0, v110, v111
	v_max3_f32 v0, v0, v112, v113
	v_max_f32_e32 v177, v177, v0
	v_mov_b32_e32 v0, v177
	v_mov_b32_e32 v221, 1.0
	s_nop 0
	v_permlane32_swap_b32_e32 v177, v0
	v_max_f32_e32 v177, v177, v0
	v_cmp_ge_f32_e32 vcc, s90, v177
	s_cmp_eq_u64 vcc, exec
	s_cbranch_scc0 .Lmla_h0_newmax
; __device__ __forceinline__ void finishSM9(f32x16& p0, f32x16& p1, float alpha, float& l_reg, v8i32& p8) {
; #pragma unroll
;   for (int r = 0; r < 16; ++r) { p0[r] = __builtin_amdgcn_exp2f(p0[r]); p1[r] = __builtin_amdgcn_exp2f(p1[r]); }
;   float ps = 0;
; #pragma unroll
;   for (int r = 0; r < 16; ++r) ps += p0[r];
; #pragma unroll
;   for (int r = 0; r < 16; ++r) ps += p1[r];
;   { auto rr = __builtin_amdgcn_permlane32_swap(__float_as_uint(ps), __float_as_uint(ps), false, false);
;     ps = __uint_as_float(rr[0]) + __uint_as_float(rr[1]); }
;   l_reg = l_reg * alpha + ps;
; #pragma unroll
;   for (int g = 0; g < 4; ++g) {
;     int w = __builtin_amdgcn_cvt_pk_fp8_f32(p0[4 * g], p0[4 * g + 1], 0, false); p8[g] = __builtin_amdgcn_cvt_pk_fp8_f32(p0[4 * g + 2], p0[4 * g + 3], w, true);
;     int u = __builtin_amdgcn_cvt_pk_fp8_f32(p1[4 * g], p1[4 * g + 1], 0, false); p8[4 + g] = __builtin_amdgcn_cvt_pk_fp8_f32(p1[4 * g + 2], p1[4 * g + 3], u, true); }
; }
; __device__ __forceinline__ void pv8(f32x16* o, const char* Vt, const v8i32 p8, int r32, int hi) {
;   const int sw = (r32 >> 2) & 3, a0 = r32 * 64 + (((hi * 2) ^ sw) << 4), a1 = r32 * 64 + (((hi * 2 + 1) ^ sw) << 4);
; #pragma unroll
;   for (int d0 = 0; d0 < 4; ++d0) {
;     const v8i32 vf = cat8(*reinterpret_cast<const v4i32*>(Vt + d0 * 2048 + a0), *reinterpret_cast<const v4i32*>(Vt + d0 * 2048 + a1));
;     o[d0] = __builtin_amdgcn_mfma_scale_f32_32x32x64_f8f6f4(p8, vf, o[d0], 0, 0, 0, 127, 0, 127); }
; }
; __device__ __forceinline__ void qkt9(f32x16& p0, f32x16& p1, const char* Kn, const char* Kr, const v8i32* qf, const float init, int r32, int hi) {
; #pragma unroll
;   for (int r = 0; r < 16; ++r) { p0[r] = init; p1[r] = init; }
; #pragma unroll
;   for (int s = 0; s < 2; ++s) { const int c0 = s * 4 + hi * 2;
;     const v8i32 a0 = cat8(*reinterpret_cast<const v4i32*>(Kn + KN8SW(r32, c0)), *reinterpret_cast<const v4i32*>(Kn + KN8SW(r32, c0 + 1)));
;     const v8i32 a1 = cat8(*reinterpret_cast<const v4i32*>(Kn + 4096 + KN8SW(r32, c0)), *reinterpret_cast<const v4i32*>(Kn + 4096 + KN8SW(r32, c0 + 1)));
;     p0 = __builtin_amdgcn_mfma_scale_f32_32x32x64_f8f6f4(a0, qf[s], p0, 0, 0, 0, 127, 0, 124);
;     p1 = __builtin_amdgcn_mfma_scale_f32_32x32x64_f8f6f4(a1, qf[s], p1, 0, 0, 0, 127, 0, 124); }
;   { const int c0 = hi * 2;
.Lmla_h0_cont:
	ds_read_b128 v[82:85], v215 offset:51200
	ds_read_b128 v[86:89], v216 offset:51200
	ds_read_b128 v[222:225], v215 offset:55296
	ds_read_b128 v[226:229], v216 offset:55296
	global_load_dwordx4 v[158:161], v176, s[18:19]
	global_load_dwordx4 v[162:165], v178, s[16:17]
	global_load_dwordx4 v[154:157], v[180:181], off
	v_add_u32_e32 v176, 0x2000, v176
	v_add_u32_e32 v178, 0x20000, v178
	s_mov_b64 s[20:21], 0x1000
	v_lshl_add_u64 v[180:181], v[180:181], 0, s[20:21]
	v_exp_f32_e32 v0, v114
	v_exp_f32_e32 v177, v115
	v_exp_f32_e32 v179, v116
	v_exp_f32_e32 v254, v117
	v_add_f32_e32 v219, v0, v177
	v_cvt_pk_fp8_f32 v246, v0, v177
	v_add_f32_e32 v219, v179, v219
	v_add_f32_e32 v219, v254, v219
	v_cvt_pk_fp8_f32 v246, v179, v254 op_sel:[0,0,1]
	s_waitcnt lgkmcnt(2)
	v_mfma_scale_f32_32x32x64_f8f6f4 v[82:97], v[82:89], v[146:153], v[230:245], v194, v193 op_sel_hi:[0,0,0]
	v_exp_f32_e32 v0, v118
	v_exp_f32_e32 v177, v119
	v_exp_f32_e32 v179, v120
	v_exp_f32_e32 v254, v121
	v_add_f32_e32 v219, v0, v219
	v_add_f32_e32 v219, v177, v219
	v_cvt_pk_fp8_f32 v247, v0, v177
	v_add_f32_e32 v219, v179, v219
	v_add_f32_e32 v219, v254, v219
	v_cvt_pk_fp8_f32 v247, v179, v254 op_sel:[0,0,1]
	ds_read_b128 v[114:117], v213 offset:51200
	ds_read_b128 v[118:121], v214 offset:51200
	s_waitcnt lgkmcnt(2)
	v_mfma_scale_f32_32x32x64_f8f6f4 v[66:81], v[222:229], v[146:153], v[230:245], v194, v193 op_sel_hi:[0,0,0]
	ds_read_b128 v[222:225], v213 offset:55296
	ds_read_b128 v[226:229], v214 offset:55296
	v_exp_f32_e32 v0, v122
	v_exp_f32_e32 v177, v123
	v_exp_f32_e32 v179, v124
	v_exp_f32_e32 v254, v125
	v_add_f32_e32 v219, v0, v219
	v_add_f32_e32 v219, v177, v219
	v_cvt_pk_fp8_f32 v248, v0, v177
	v_add_f32_e32 v219, v179, v219
	v_add_f32_e32 v219, v254, v219
	v_cvt_pk_fp8_f32 v248, v179, v254 op_sel:[0,0,1]
	v_exp_f32_e32 v0, v126
	v_exp_f32_e32 v177, v127
	v_exp_f32_e32 v179, v128
	v_exp_f32_e32 v254, v129
	v_add_f32_e32 v219, v0, v219
	v_add_f32_e32 v219, v177, v219
	v_cvt_pk_fp8_f32 v249, v0, v177
	v_add_f32_e32 v219, v179, v219
	v_add_f32_e32 v219, v254, v219
	v_cvt_pk_fp8_f32 v249, v179, v254 op_sel:[0,0,1]
	ds_read_b128 v[122:125], v185 offset:59392
	ds_read_b128 v[126:129], v186 offset:59392
	s_waitcnt lgkmcnt(4)
	v_mfma_scale_f32_32x32x64_f8f6f4 v[82:97], v[114:121], v[138:145], v[82:97], v194, v193 op_sel_hi:[0,0,0]
	v_exp_f32_e32 v0, v98
	v_exp_f32_e32 v177, v99
	v_exp_f32_e32 v179, v100
	v_exp_f32_e32 v254, v101
	v_add_f32_e32 v219, v0, v219
	v_add_f32_e32 v219, v177, v219
	v_cvt_pk_fp8_f32 v250, v0, v177
	v_add_f32_e32 v219, v179, v219
	v_add_f32_e32 v219, v254, v219
	v_cvt_pk_fp8_f32 v250, v179, v254 op_sel:[0,0,1]
	s_waitcnt lgkmcnt(2)
	v_mfma_scale_f32_32x32x64_f8f6f4 v[66:81], v[222:229], v[138:145], v[66:81], v194, v193 op_sel_hi:[0,0,0]
	ds_read_b128 v[222:225], v185 offset:61440
	ds_read_b128 v[226:229], v186 offset:61440
	v_exp_f32_e32 v0, v102
	v_exp_f32_e32 v177, v103
	v_exp_f32_e32 v179, v104
	v_exp_f32_e32 v254, v105
	v_add_f32_e32 v219, v0, v219
	v_add_f32_e32 v219, v177, v219
	v_cvt_pk_fp8_f32 v251, v0, v177
	v_add_f32_e32 v219, v179, v219
	v_add_f32_e32 v219, v254, v219
	v_cvt_pk_fp8_f32 v251, v179, v254 op_sel:[0,0,1]
	v_exp_f32_e32 v0, v106
	v_exp_f32_e32 v177, v107
	v_exp_f32_e32 v179, v108
	v_exp_f32_e32 v254, v109
	v_add_f32_e32 v219, v0, v219
	v_add_f32_e32 v219, v177, v219
	v_cvt_pk_fp8_f32 v252, v0, v177
	v_add_f32_e32 v219, v179, v219
	v_add_f32_e32 v219, v254, v219
	v_cvt_pk_fp8_f32 v252, v179, v254 op_sel:[0,0,1]
	s_waitcnt lgkmcnt(2)
	v_mfma_scale_f32_32x32x64_f8f6f4 v[82:97], v[122:129], v[130:137], v[82:97], v194, v193 op_sel_hi:[0,0,0]
	v_exp_f32_e32 v0, v110
	v_exp_f32_e32 v177, v111
	v_exp_f32_e32 v179, v112
	v_exp_f32_e32 v254, v113
	v_add_f32_e32 v219, v0, v219
	v_add_f32_e32 v219, v177, v219
	v_cvt_pk_fp8_f32 v253, v0, v177
	v_add_f32_e32 v219, v179, v219
	v_add_f32_e32 v219, v254, v219
	v_cvt_pk_fp8_f32 v253, v179, v254 op_sel:[0,0,1]
	ds_read_b128 v[122:125], v185 offset:8192
	ds_read_b128 v[126:129], v186 offset:8192
	ds_read_b128 v[114:117], v185 offset:10240
	ds_read_b128 v[118:121], v186 offset:10240
	ds_read_b128 v[106:109], v185 offset:12288
	ds_read_b128 v[110:113], v186 offset:12288
	ds_read_b128 v[98:101], v185 offset:14336
	ds_read_b128 v[102:105], v186 offset:14336
	s_waitcnt lgkmcnt(8)
	v_mfma_scale_f32_32x32x64_f8f6f4 v[66:81], v[222:229], v[130:137], v[66:81], v194, v193 op_sel_hi:[0,0,0]
	v_mov_b32_e32 v0, v219
	s_nop 1
	v_permlane32_swap_b32_e32 v219, v0
	v_add_f32_e32 v219, v219, v0
	v_fma_f32 v209, v209, v221, v219
	v_max_f32_e32 v177, v82, v83
	v_max3_f32 v177, v177, v84, v85
	v_max3_f32 v177, v177, v86, v87
	v_max3_f32 v177, v177, v88, v89
	v_max3_f32 v177, v177, v90, v91
	v_max3_f32 v177, v177, v92, v93
	v_max3_f32 v177, v177, v94, v95
	v_max3_f32 v177, v177, v96, v97
	s_waitcnt lgkmcnt(6)
	v_mfma_scale_f32_32x32x64_f8f6f4 v[50:65], v[246:253], v[122:129], v[50:65], v194, v194 op_sel_hi:[0,0,0]
	s_waitcnt vmcnt(0)
	ds_write_b128 v210, v[158:161]
	ds_write_b128 v211, v[162:165] offset:16384
	ds_write_b128 v212, v[154:157] offset:32768
	s_waitcnt lgkmcnt(7)
	v_mfma_scale_f32_32x32x64_f8f6f4 v[34:49], v[246:253], v[114:121], v[34:49], v194, v194 op_sel_hi:[0,0,0]
	s_waitcnt lgkmcnt(0)
	s_barrier
	s_waitcnt lgkmcnt(2)
	v_mfma_scale_f32_32x32x64_f8f6f4 v[18:33], v[246:253], v[106:113], v[18:33], v194, v194 op_sel_hi:[0,0,0]
	s_waitcnt lgkmcnt(0)
	v_mfma_scale_f32_32x32x64_f8f6f4 v[2:17], v[246:253], v[98:105], v[2:17], v194, v194 op_sel_hi:[0,0,0]
	v_max_f32_e32 v0, v66, v67
	v_max3_f32 v0, v0, v68, v69
	v_max3_f32 v0, v0, v70, v71
	v_max3_f32 v0, v0, v72, v73
	v_max3_f32 v0, v0, v74, v75
	v_max3_f32 v0, v0, v76, v77
	v_max3_f32 v0, v0, v78, v79
	v_max3_f32 v0, v0, v80, v81
	v_max_f32_e32 v177, v177, v0
	v_mov_b32_e32 v0, v177
	v_mov_b32_e32 v218, 1.0
	s_nop 0
	v_permlane32_swap_b32_e32 v177, v0
	v_max_f32_e32 v177, v177, v0
	v_cmp_ge_f32_e32 vcc, s90, v177
	s_cmp_eq_u64 vcc, exec
	s_cbranch_scc0 .Lmla_h1_newmax
; __device__ __forceinline__ void finishSM9(f32x16& p0, f32x16& p1, float alpha, float& l_reg, v8i32& p8) {
; #pragma unroll
;   for (int r = 0; r < 16; ++r) { p0[r] = __builtin_amdgcn_exp2f(p0[r]); p1[r] = __builtin_amdgcn_exp2f(p1[r]); }
;   float ps = 0;
; #pragma unroll
;   for (int r = 0; r < 16; ++r) ps += p0[r];
; #pragma unroll
;   for (int r = 0; r < 16; ++r) ps += p1[r];
;   { auto rr = __builtin_amdgcn_permlane32_swap(__float_as_uint(ps), __float_as_uint(ps), false, false);
;     ps = __uint_as_float(rr[0]) + __uint_as_float(rr[1]); }
;   l_reg = l_reg * alpha + ps;
; #pragma unroll
;   for (int g = 0; g < 4; ++g) {
;     int w = __builtin_amdgcn_cvt_pk_fp8_f32(p0[4 * g], p0[4 * g + 1], 0, false); p8[g] = __builtin_amdgcn_cvt_pk_fp8_f32(p0[4 * g + 2], p0[4 * g + 3], w, true);
;     int u = __builtin_amdgcn_cvt_pk_fp8_f32(p1[4 * g], p1[4 * g + 1], 0, false); p8[4 + g] = __builtin_amdgcn_cvt_pk_fp8_f32(p1[4 * g + 2], p1[4 * g + 3], u, true); }
; }
; __device__ __forceinline__ void pv8(f32x16* o, const char* Vt, const v8i32 p8, int r32, int hi) {
;   const int sw = (r32 >> 2) & 3, a0 = r32 * 64 + (((hi * 2) ^ sw) << 4), a1 = r32 * 64 + (((hi * 2 + 1) ^ sw) << 4);
; #pragma unroll
;   for (int d0 = 0; d0 < 4; ++d0) {
;     const v8i32 vf = cat8(*reinterpret_cast<const v4i32*>(Vt + d0 * 2048 + a0), *reinterpret_cast<const v4i32*>(Vt + d0 * 2048 + a1));
;     o[d0] = __builtin_amdgcn_mfma_scale_f32_32x32x64_f8f6f4(p8, vf, o[d0], 0, 0, 0, 127, 0, 127); }
; }
; __device__ __forceinline__ void qkt9(f32x16& p0, f32x16& p1, const char* Kn, const char* Kr, const v8i32* qf, const float init, int r32, int hi) {
; #pragma unroll
;   for (int r = 0; r < 16; ++r) { p0[r] = init; p1[r] = init; }
; #pragma unroll
;   for (int s = 0; s < 2; ++s) { const int c0 = s * 4 + hi * 2;
;     const v8i32 a0 = cat8(*reinterpret_cast<const v4i32*>(Kn + KN8SW(r32, c0)), *reinterpret_cast<const v4i32*>(Kn + KN8SW(r32, c0 + 1)));
;     const v8i32 a1 = cat8(*reinterpret_cast<const v4i32*>(Kn + 4096 + KN8SW(r32, c0)), *reinterpret_cast<const v4i32*>(Kn + 4096 + KN8SW(r32, c0 + 1)));
;     p0 = __builtin_amdgcn_mfma_scale_f32_32x32x64_f8f6f4(a0, qf[s], p0, 0, 0, 0, 127, 0, 124);
;     p1 = __builtin_amdgcn_mfma_scale_f32_32x32x64_f8f6f4(a1, qf[s], p1, 0, 0, 0, 127, 0, 124); }
;   { const int c0 = hi * 2;
.Lmla_h1_cont:
	ds_read_b128 v[114:117], v215 offset:16384
	ds_read_b128 v[118:121], v216 offset:16384
	ds_read_b128 v[222:225], v215 offset:20480
	ds_read_b128 v[226:229], v216 offset:20480
	global_load_dwordx4 v[158:161], v176, s[18:19]
	global_load_dwordx4 v[162:165], v178, s[16:17]
	global_load_dwordx4 v[154:157], v[180:181], off
	v_add_u32_e32 v176, 0x2000, v176
	v_add_u32_e32 v178, 0x20000, v178
	s_mov_b64 s[20:21], 0x1000
	v_lshl_add_u64 v[180:181], v[180:181], 0, s[20:21]
	v_exp_f32_e32 v0, v82
	v_exp_f32_e32 v177, v83
	v_exp_f32_e32 v179, v84
	v_exp_f32_e32 v254, v85
	v_add_f32_e32 v219, v0, v177
	v_cvt_pk_fp8_f32 v246, v0, v177
	v_add_f32_e32 v219, v179, v219
	v_add_f32_e32 v219, v254, v219
	v_cvt_pk_fp8_f32 v246, v179, v254 op_sel:[0,0,1]
	s_waitcnt lgkmcnt(2)
	v_mfma_scale_f32_32x32x64_f8f6f4 v[114:129], v[114:121], v[146:153], v[230:245], v194, v193 op_sel_hi:[0,0,0]
	v_exp_f32_e32 v0, v86
	v_exp_f32_e32 v177, v87
	v_exp_f32_e32 v179, v88
	v_exp_f32_e32 v254, v89
	v_add_f32_e32 v219, v0, v219
	v_add_f32_e32 v219, v177, v219
	v_cvt_pk_fp8_f32 v247, v0, v177
	v_add_f32_e32 v219, v179, v219
	v_add_f32_e32 v219, v254, v219
	v_cvt_pk_fp8_f32 v247, v179, v254 op_sel:[0,0,1]
	ds_read_b128 v[82:85], v213 offset:16384
	ds_read_b128 v[86:89], v214 offset:16384
	s_waitcnt lgkmcnt(2)
	v_mfma_scale_f32_32x32x64_f8f6f4 v[98:113], v[222:229], v[146:153], v[230:245], v194, v193 op_sel_hi:[0,0,0]
	ds_read_b128 v[222:225], v213 offset:20480
	ds_read_b128 v[226:229], v214 offset:20480
	v_exp_f32_e32 v0, v90
	v_exp_f32_e32 v177, v91
	v_exp_f32_e32 v179, v92
	v_exp_f32_e32 v254, v93
	v_add_f32_e32 v219, v0, v219
	v_add_f32_e32 v219, v177, v219
	v_cvt_pk_fp8_f32 v248, v0, v177
	v_add_f32_e32 v219, v179, v219
	v_add_f32_e32 v219, v254, v219
	v_cvt_pk_fp8_f32 v248, v179, v254 op_sel:[0,0,1]
	v_exp_f32_e32 v0, v94
	v_exp_f32_e32 v177, v95
	v_exp_f32_e32 v179, v96
	v_exp_f32_e32 v254, v97
	v_add_f32_e32 v219, v0, v219
	v_add_f32_e32 v219, v177, v219
	v_cvt_pk_fp8_f32 v249, v0, v177
	v_add_f32_e32 v219, v179, v219
	v_add_f32_e32 v219, v254, v219
	v_cvt_pk_fp8_f32 v249, v179, v254 op_sel:[0,0,1]
	ds_read_b128 v[90:93], v185 offset:32768
	ds_read_b128 v[94:97], v186 offset:32768
	s_waitcnt lgkmcnt(4)
	v_mfma_scale_f32_32x32x64_f8f6f4 v[114:129], v[82:89], v[138:145], v[114:129], v194, v193 op_sel_hi:[0,0,0]
	v_exp_f32_e32 v0, v66
	v_exp_f32_e32 v177, v67
	v_exp_f32_e32 v179, v68
	v_exp_f32_e32 v254, v69
	v_add_f32_e32 v219, v0, v219
	v_add_f32_e32 v219, v177, v219
	v_cvt_pk_fp8_f32 v250, v0, v177
	v_add_f32_e32 v219, v179, v219
	v_add_f32_e32 v219, v254, v219
	v_cvt_pk_fp8_f32 v250, v179, v254 op_sel:[0,0,1]
	s_waitcnt lgkmcnt(2)
	v_mfma_scale_f32_32x32x64_f8f6f4 v[98:113], v[222:229], v[138:145], v[98:113], v194, v193 op_sel_hi:[0,0,0]
	ds_read_b128 v[222:225], v185 offset:34816
	ds_read_b128 v[226:229], v186 offset:34816
	v_exp_f32_e32 v0, v70
	v_exp_f32_e32 v177, v71
	v_exp_f32_e32 v179, v72
	v_exp_f32_e32 v254, v73
	v_add_f32_e32 v219, v0, v219
	v_add_f32_e32 v219, v177, v219
	v_cvt_pk_fp8_f32 v251, v0, v177
	v_add_f32_e32 v219, v179, v219
	v_add_f32_e32 v219, v254, v219
	v_cvt_pk_fp8_f32 v251, v179, v254 op_sel:[0,0,1]
	v_exp_f32_e32 v0, v74
	v_exp_f32_e32 v177, v75
	v_exp_f32_e32 v179, v76
	v_exp_f32_e32 v254, v77
	v_add_f32_e32 v219, v0, v219
	v_add_f32_e32 v219, v177, v219
	v_cvt_pk_fp8_f32 v252, v0, v177
	v_add_f32_e32 v219, v179, v219
	v_add_f32_e32 v219, v254, v219
	v_cvt_pk_fp8_f32 v252, v179, v254 op_sel:[0,0,1]
	s_waitcnt lgkmcnt(2)
	v_mfma_scale_f32_32x32x64_f8f6f4 v[114:129], v[90:97], v[130:137], v[114:129], v194, v193 op_sel_hi:[0,0,0]
	v_exp_f32_e32 v0, v78
	v_exp_f32_e32 v177, v79
	v_exp_f32_e32 v179, v80
	v_exp_f32_e32 v254, v81
	v_add_f32_e32 v219, v0, v219
	v_add_f32_e32 v219, v177, v219
	v_cvt_pk_fp8_f32 v253, v0, v177
	v_add_f32_e32 v219, v179, v219
	v_add_f32_e32 v219, v254, v219
	v_cvt_pk_fp8_f32 v253, v179, v254 op_sel:[0,0,1]
	ds_read_b128 v[90:93], v185 offset:43008
	ds_read_b128 v[94:97], v186 offset:43008
	ds_read_b128 v[82:85], v185 offset:45056
	ds_read_b128 v[86:89], v186 offset:45056
	ds_read_b128 v[74:77], v185 offset:47104
	ds_read_b128 v[78:81], v186 offset:47104
	ds_read_b128 v[66:69], v185 offset:49152
	ds_read_b128 v[70:73], v186 offset:49152
	s_waitcnt lgkmcnt(8)
	v_mfma_scale_f32_32x32x64_f8f6f4 v[98:113], v[222:229], v[130:137], v[98:113], v194, v193 op_sel_hi:[0,0,0]
	v_mov_b32_e32 v0, v219
	s_nop 1
	v_permlane32_swap_b32_e32 v219, v0
	v_add_f32_e32 v219, v219, v0
	v_fma_f32 v209, v209, v218, v219
	v_max_f32_e32 v177, v114, v115
	v_max3_f32 v177, v177, v116, v117
	v_max3_f32 v177, v177, v118, v119
	v_max3_f32 v177, v177, v120, v121
	v_max3_f32 v177, v177, v122, v123
	v_max3_f32 v177, v177, v124, v125
	v_max3_f32 v177, v177, v126, v127
	v_max3_f32 v177, v177, v128, v129
	s_waitcnt lgkmcnt(6)
	v_mfma_scale_f32_32x32x64_f8f6f4 v[50:65], v[246:253], v[90:97], v[50:65], v194, v194 op_sel_hi:[0,0,0]
	s_waitcnt vmcnt(0)
	ds_write_b128 v210, v[158:161] offset:8192
	ds_write_b128 v211, v[162:165] offset:24576
	ds_write_b128 v212, v[154:157] offset:36864
	s_waitcnt lgkmcnt(7)
	v_mfma_scale_f32_32x32x64_f8f6f4 v[34:49], v[246:253], v[82:89], v[34:49], v194, v194 op_sel_hi:[0,0,0]
	s_waitcnt lgkmcnt(0)
	s_barrier
	s_waitcnt lgkmcnt(2)
	v_mfma_scale_f32_32x32x64_f8f6f4 v[18:33], v[246:253], v[74:81], v[18:33], v194, v194 op_sel_hi:[0,0,0]
	s_waitcnt lgkmcnt(0)
	v_mfma_scale_f32_32x32x64_f8f6f4 v[2:17], v[246:253], v[66:73], v[2:17], v194, v194 op_sel_hi:[0,0,0]
	v_max_f32_e32 v0, v98, v99
	v_max3_f32 v0, v0, v100, v101
	v_max3_f32 v0, v0, v102, v103
	v_max3_f32 v0, v0, v104, v105
	v_max3_f32 v0, v0, v106, v107
	v_max3_f32 v0, v0, v108, v109
	v_max3_f32 v0, v0, v110, v111
	v_max3_f32 v0, v0, v112, v113
	v_max_f32_e32 v177, v177, v0
	v_mov_b32_e32 v0, v177
	v_mov_b32_e32 v221, 1.0
	s_nop 0
	v_permlane32_swap_b32_e32 v177, v0
	v_max_f32_e32 v177, v177, v0
	v_cmp_ge_f32_e32 vcc, s90, v177
	s_cmp_eq_u64 vcc, exec
	s_cbranch_scc0 .Lmla_h2_newmax
; __device__ __forceinline__ void finishSM9(f32x16& p0, f32x16& p1, float alpha, float& l_reg, v8i32& p8) {
; #pragma unroll
;   for (int r = 0; r < 16; ++r) { p0[r] = __builtin_amdgcn_exp2f(p0[r]); p1[r] = __builtin_amdgcn_exp2f(p1[r]); }
;   float ps = 0;
; #pragma unroll
;   for (int r = 0; r < 16; ++r) ps += p0[r];
; #pragma unroll
;   for (int r = 0; r < 16; ++r) ps += p1[r];
;   { auto rr = __builtin_amdgcn_permlane32_swap(__float_as_uint(ps), __float_as_uint(ps), false, false);
;     ps = __uint_as_float(rr[0]) + __uint_as_float(rr[1]); }
;   l_reg = l_reg * alpha + ps;
; #pragma unroll
;   for (int g = 0; g < 4; ++g) {
;     int w = __builtin_amdgcn_cvt_pk_fp8_f32(p0[4 * g], p0[4 * g + 1], 0, false); p8[g] = __builtin_amdgcn_cvt_pk_fp8_f32(p0[4 * g + 2], p0[4 * g + 3], w, true);
;     int u = __builtin_amdgcn_cvt_pk_fp8_f32(p1[4 * g], p1[4 * g + 1], 0, false); p8[4 + g] = __builtin_amdgcn_cvt_pk_fp8_f32(p1[4 * g + 2], p1[4 * g + 3], u, true); }
; }
; __device__ __forceinline__ void pv8(f32x16* o, const char* Vt, const v8i32 p8, int r32, int hi) {
;   const int sw = (r32 >> 2) & 3, a0 = r32 * 64 + (((hi * 2) ^ sw) << 4), a1 = r32 * 64 + (((hi * 2 + 1) ^ sw) << 4);
; #pragma unroll
;   for (int d0 = 0; d0 < 4; ++d0) {
;     const v8i32 vf = cat8(*reinterpret_cast<const v4i32*>(Vt + d0 * 2048 + a0), *reinterpret_cast<const v4i32*>(Vt + d0 * 2048 + a1));
;     o[d0] = __builtin_amdgcn_mfma_scale_f32_32x32x64_f8f6f4(p8, vf, o[d0], 0, 0, 0, 127, 0, 127); }
; }
; __device__ __forceinline__ void qkt9(f32x16& p0, f32x16& p1, const char* Kn, const char* Kr, const v8i32* qf, const float init, int r32, int hi) {
; #pragma unroll
;   for (int r = 0; r < 16; ++r) { p0[r] = init; p1[r] = init; }
; #pragma unroll
;   for (int s = 0; s < 2; ++s) { const int c0 = s * 4 + hi * 2;
;     const v8i32 a0 = cat8(*reinterpret_cast<const v4i32*>(Kn + KN8SW(r32, c0)), *reinterpret_cast<const v4i32*>(Kn + KN8SW(r32, c0 + 1)));
;     const v8i32 a1 = cat8(*reinterpret_cast<const v4i32*>(Kn + 4096 + KN8SW(r32, c0)), *reinterpret_cast<const v4i32*>(Kn + 4096 + KN8SW(r32, c0 + 1)));
;     p0 = __builtin_amdgcn_mfma_scale_f32_32x32x64_f8f6f4(a0, qf[s], p0, 0, 0, 0, 127, 0, 124);
;     p1 = __builtin_amdgcn_mfma_scale_f32_32x32x64_f8f6f4(a1, qf[s], p1, 0, 0, 0, 127, 0, 124); }
;   { const int c0 = hi * 2;
.Lmla_h2_cont:
	ds_read_b128 v[82:85], v215 offset:24576
	ds_read_b128 v[86:89], v216 offset:24576
	ds_read_b128 v[222:225], v215 offset:28672
	ds_read_b128 v[226:229], v216 offset:28672
	global_load_dwordx4 v[158:161], v176, s[18:19]
	global_load_dwordx4 v[162:165], v178, s[16:17]
	global_load_dwordx4 v[154:157], v[180:181], off
	v_add_u32_e32 v176, 0x2000, v176
	v_add_u32_e32 v178, 0x20000, v178
	s_mov_b64 s[20:21], 0x1000
	v_lshl_add_u64 v[180:181], v[180:181], 0, s[20:21]
	v_exp_f32_e32 v0, v114
	v_exp_f32_e32 v177, v115
	v_exp_f32_e32 v179, v116
	v_exp_f32_e32 v254, v117
	v_add_f32_e32 v219, v0, v177
	v_cvt_pk_fp8_f32 v246, v0, v177
	v_add_f32_e32 v219, v179, v219
	v_add_f32_e32 v219, v254, v219
	v_cvt_pk_fp8_f32 v246, v179, v254 op_sel:[0,0,1]
	s_waitcnt lgkmcnt(2)
	v_mfma_scale_f32_32x32x64_f8f6f4 v[82:97], v[82:89], v[146:153], v[230:245], v194, v193 op_sel_hi:[0,0,0]
	v_exp_f32_e32 v0, v118
	v_exp_f32_e32 v177, v119
	v_exp_f32_e32 v179, v120
	v_exp_f32_e32 v254, v121
	v_add_f32_e32 v219, v0, v219
	v_add_f32_e32 v219, v177, v219
	v_cvt_pk_fp8_f32 v247, v0, v177
	v_add_f32_e32 v219, v179, v219
	v_add_f32_e32 v219, v254, v219
	v_cvt_pk_fp8_f32 v247, v179, v254 op_sel:[0,0,1]
	ds_read_b128 v[114:117], v213 offset:24576
	ds_read_b128 v[118:121], v214 offset:24576
	s_waitcnt lgkmcnt(2)
	v_mfma_scale_f32_32x32x64_f8f6f4 v[66:81], v[222:229], v[146:153], v[230:245], v194, v193 op_sel_hi:[0,0,0]
	ds_read_b128 v[222:225], v213 offset:28672
	ds_read_b128 v[226:229], v214 offset:28672
	v_exp_f32_e32 v0, v122
	v_exp_f32_e32 v177, v123
	v_exp_f32_e32 v179, v124
	v_exp_f32_e32 v254, v125
	v_add_f32_e32 v219, v0, v219
	v_add_f32_e32 v219, v177, v219
	v_cvt_pk_fp8_f32 v248, v0, v177
	v_add_f32_e32 v219, v179, v219
	v_add_f32_e32 v219, v254, v219
	v_cvt_pk_fp8_f32 v248, v179, v254 op_sel:[0,0,1]
	v_exp_f32_e32 v0, v126
	v_exp_f32_e32 v177, v127
	v_exp_f32_e32 v179, v128
	v_exp_f32_e32 v254, v129
	v_add_f32_e32 v219, v0, v219
	v_add_f32_e32 v219, v177, v219
	v_cvt_pk_fp8_f32 v249, v0, v177
	v_add_f32_e32 v219, v179, v219
	v_add_f32_e32 v219, v254, v219
	v_cvt_pk_fp8_f32 v249, v179, v254 op_sel:[0,0,1]
	ds_read_b128 v[122:125], v185 offset:36864
	ds_read_b128 v[126:129], v186 offset:36864
	s_waitcnt lgkmcnt(4)
	v_mfma_scale_f32_32x32x64_f8f6f4 v[82:97], v[114:121], v[138:145], v[82:97], v194, v193 op_sel_hi:[0,0,0]
	v_exp_f32_e32 v0, v98
	v_exp_f32_e32 v177, v99
	v_exp_f32_e32 v179, v100
	v_exp_f32_e32 v254, v101
	v_add_f32_e32 v219, v0, v219
	v_add_f32_e32 v219, v177, v219
	v_cvt_pk_fp8_f32 v250, v0, v177
	v_add_f32_e32 v219, v179, v219
	v_add_f32_e32 v219, v254, v219
	v_cvt_pk_fp8_f32 v250, v179, v254 op_sel:[0,0,1]
	s_waitcnt lgkmcnt(2)
	v_mfma_scale_f32_32x32x64_f8f6f4 v[66:81], v[222:229], v[138:145], v[66:81], v194, v193 op_sel_hi:[0,0,0]
	ds_read_b128 v[222:225], v185 offset:38912
	ds_read_b128 v[226:229], v186 offset:38912
	v_exp_f32_e32 v0, v102
	v_exp_f32_e32 v177, v103
	v_exp_f32_e32 v179, v104
	v_exp_f32_e32 v254, v105
	v_add_f32_e32 v219, v0, v219
	v_add_f32_e32 v219, v177, v219
	v_cvt_pk_fp8_f32 v251, v0, v177
	v_add_f32_e32 v219, v179, v219
	v_add_f32_e32 v219, v254, v219
	v_cvt_pk_fp8_f32 v251, v179, v254 op_sel:[0,0,1]
	v_exp_f32_e32 v0, v106
	v_exp_f32_e32 v177, v107
	v_exp_f32_e32 v179, v108
	v_exp_f32_e32 v254, v109
	v_add_f32_e32 v219, v0, v219
	v_add_f32_e32 v219, v177, v219
	v_cvt_pk_fp8_f32 v252, v0, v177
	v_add_f32_e32 v219, v179, v219
	v_add_f32_e32 v219, v254, v219
	v_cvt_pk_fp8_f32 v252, v179, v254 op_sel:[0,0,1]
	s_waitcnt lgkmcnt(2)
	v_mfma_scale_f32_32x32x64_f8f6f4 v[82:97], v[122:129], v[130:137], v[82:97], v194, v193 op_sel_hi:[0,0,0]
	v_exp_f32_e32 v0, v110
	v_exp_f32_e32 v177, v111
	v_exp_f32_e32 v179, v112
	v_exp_f32_e32 v254, v113
	v_add_f32_e32 v219, v0, v219
	v_add_f32_e32 v219, v177, v219
	v_cvt_pk_fp8_f32 v253, v0, v177
	v_add_f32_e32 v219, v179, v219
	v_add_f32_e32 v219, v254, v219
	v_cvt_pk_fp8_f32 v253, v179, v254 op_sel:[0,0,1]
	ds_read_b128 v[122:125], v185 offset:0
	ds_read_b128 v[126:129], v186 offset:0
	ds_read_b128 v[114:117], v185 offset:2048
	ds_read_b128 v[118:121], v186 offset:2048
	ds_read_b128 v[106:109], v185 offset:4096
	ds_read_b128 v[110:113], v186 offset:4096
	ds_read_b128 v[98:101], v185 offset:6144
	ds_read_b128 v[102:105], v186 offset:6144
	s_waitcnt lgkmcnt(8)
	v_mfma_scale_f32_32x32x64_f8f6f4 v[66:81], v[222:229], v[130:137], v[66:81], v194, v193 op_sel_hi:[0,0,0]
	v_mov_b32_e32 v0, v219
	s_nop 1
	v_permlane32_swap_b32_e32 v219, v0
	v_add_f32_e32 v219, v219, v0
	v_fma_f32 v209, v209, v221, v219
	v_max_f32_e32 v177, v82, v83
	v_max3_f32 v177, v177, v84, v85
	v_max3_f32 v177, v177, v86, v87
	v_max3_f32 v177, v177, v88, v89
	v_max3_f32 v177, v177, v90, v91
	v_max3_f32 v177, v177, v92, v93
	v_max3_f32 v177, v177, v94, v95
	v_max3_f32 v177, v177, v96, v97
	s_waitcnt lgkmcnt(6)
	v_mfma_scale_f32_32x32x64_f8f6f4 v[50:65], v[246:253], v[122:129], v[50:65], v194, v194 op_sel_hi:[0,0,0]
	s_waitcnt vmcnt(0)
	ds_write_b128 v210, v[158:161] offset:43008
	ds_write_b128 v211, v[162:165] offset:51200
	ds_write_b128 v212, v[154:157] offset:59392
	s_waitcnt lgkmcnt(7)
	v_mfma_scale_f32_32x32x64_f8f6f4 v[34:49], v[246:253], v[114:121], v[34:49], v194, v194 op_sel_hi:[0,0,0]
	s_waitcnt lgkmcnt(0)
	s_barrier
	s_waitcnt lgkmcnt(2)
	v_mfma_scale_f32_32x32x64_f8f6f4 v[18:33], v[246:253], v[106:113], v[18:33], v194, v194 op_sel_hi:[0,0,0]
	s_waitcnt lgkmcnt(0)
	v_mfma_scale_f32_32x32x64_f8f6f4 v[2:17], v[246:253], v[98:105], v[2:17], v194, v194 op_sel_hi:[0,0,0]
	v_max_f32_e32 v0, v66, v67
	v_max3_f32 v0, v0, v68, v69
	v_max3_f32 v0, v0, v70, v71
	v_max3_f32 v0, v0, v72, v73
	v_max3_f32 v0, v0, v74, v75
	v_max3_f32 v0, v0, v76, v77
	v_max3_f32 v0, v0, v78, v79
	v_max3_f32 v0, v0, v80, v81
	v_max_f32_e32 v177, v177, v0
	v_mov_b32_e32 v0, v177
	v_mov_b32_e32 v218, 1.0
	s_nop 0
	v_permlane32_swap_b32_e32 v177, v0
	v_max_f32_e32 v177, v177, v0
	v_cmp_ge_f32_e32 vcc, s90, v177
	s_cmp_eq_u64 vcc, exec
	s_cbranch_scc0 .Lmla_h3_newmax
; __device__ __forceinline__ void finishSM9(f32x16& p0, f32x16& p1, float alpha, float& l_reg, v8i32& p8) {
; #pragma unroll
;   for (int r = 0; r < 16; ++r) { p0[r] = __builtin_amdgcn_exp2f(p0[r]); p1[r] = __builtin_amdgcn_exp2f(p1[r]); }
;   float ps = 0;
; #pragma unroll
;   for (int r = 0; r < 16; ++r) ps += p0[r];
; #pragma unroll
;   for (int r = 0; r < 16; ++r) ps += p1[r];
;   { auto rr = __builtin_amdgcn_permlane32_swap(__float_as_uint(ps), __float_as_uint(ps), false, false);
;     ps = __uint_as_float(rr[0]) + __uint_as_float(rr[1]); }
;   l_reg = l_reg * alpha + ps;
; #pragma unroll
;   for (int g = 0; g < 4; ++g) {
;     int w = __builtin_amdgcn_cvt_pk_fp8_f32(p0[4 * g], p0[4 * g + 1], 0, false); p8[g] = __builtin_amdgcn_cvt_pk_fp8_f32(p0[4 * g + 2], p0[4 * g + 3], w, true);
;     int u = __builtin_amdgcn_cvt_pk_fp8_f32(p1[4 * g], p1[4 * g + 1], 0, false); p8[4 + g] = __builtin_amdgcn_cvt_pk_fp8_f32(p1[4 * g + 2], p1[4 * g + 3], u, true); }
; }
; __device__ __forceinline__ void pv8(f32x16* o, const char* Vt, const v8i32 p8, int r32, int hi) {
;   const int sw = (r32 >> 2) & 3, a0 = r32 * 64 + (((hi * 2) ^ sw) << 4), a1 = r32 * 64 + (((hi * 2 + 1) ^ sw) << 4);
; #pragma unroll
;   for (int d0 = 0; d0 < 4; ++d0) {
;     const v8i32 vf = cat8(*reinterpret_cast<const v4i32*>(Vt + d0 * 2048 + a0), *reinterpret_cast<const v4i32*>(Vt + d0 * 2048 + a1));
;     o[d0] = __builtin_amdgcn_mfma_scale_f32_32x32x64_f8f6f4(p8, vf, o[d0], 0, 0, 0, 127, 0, 127); }
; }
; __device__ __forceinline__ void qkt9(f32x16& p0, f32x16& p1, const char* Kn, const char* Kr, const v8i32* qf, const float init, int r32, int hi) {
; #pragma unroll
;   for (int r = 0; r < 16; ++r) { p0[r] = init; p1[r] = init; }
; #pragma unroll
;   for (int s = 0; s < 2; ++s) { const int c0 = s * 4 + hi * 2;
;     const v8i32 a0 = cat8(*reinterpret_cast<const v4i32*>(Kn + KN8SW(r32, c0)), *reinterpret_cast<const v4i32*>(Kn + KN8SW(r32, c0 + 1)));
;     const v8i32 a1 = cat8(*reinterpret_cast<const v4i32*>(Kn + 4096 + KN8SW(r32, c0)), *reinterpret_cast<const v4i32*>(Kn + 4096 + KN8SW(r32, c0 + 1)));
;     p0 = __builtin_amdgcn_mfma_scale_f32_32x32x64_f8f6f4(a0, qf[s], p0, 0, 0, 0, 127, 0, 124);
;     p1 = __builtin_amdgcn_mfma_scale_f32_32x32x64_f8f6f4(a1, qf[s], p1, 0, 0, 0, 127, 0, 124); }
;   { const int c0 = hi * 2;
.Lmla_h3_cont:
	ds_read_b128 v[114:117], v215 offset:51200
	ds_read_b128 v[118:121], v216 offset:51200
	ds_read_b128 v[222:225], v215 offset:55296
	ds_read_b128 v[226:229], v216 offset:55296
	global_load_dwordx4 v[158:161], v176, s[18:19]
	global_load_dwordx4 v[162:165], v178, s[16:17]
	global_load_dwordx4 v[154:157], v[180:181], off
	v_add_u32_e32 v176, 0x2000, v176
	v_add_u32_e32 v178, 0x20000, v178
	s_mov_b64 s[20:21], 0x1000
	v_lshl_add_u64 v[180:181], v[180:181], 0, s[20:21]
	v_exp_f32_e32 v0, v82
	v_exp_f32_e32 v177, v83
	v_exp_f32_e32 v179, v84
	v_exp_f32_e32 v254, v85
	v_add_f32_e32 v219, v0, v177
	v_cvt_pk_fp8_f32 v246, v0, v177
	v_add_f32_e32 v219, v179, v219
	v_add_f32_e32 v219, v254, v219
	v_cvt_pk_fp8_f32 v246, v179, v254 op_sel:[0,0,1]
	s_waitcnt lgkmcnt(2)
	v_mfma_scale_f32_32x32x64_f8f6f4 v[114:129], v[114:121], v[146:153], v[230:245], v194, v193 op_sel_hi:[0,0,0]
	v_exp_f32_e32 v0, v86
	v_exp_f32_e32 v177, v87
	v_exp_f32_e32 v179, v88
	v_exp_f32_e32 v254, v89
	v_add_f32_e32 v219, v0, v219
	v_add_f32_e32 v219, v177, v219
	v_cvt_pk_fp8_f32 v247, v0, v177
	v_add_f32_e32 v219, v179, v219
	v_add_f32_e32 v219, v254, v219
	v_cvt_pk_fp8_f32 v247, v179, v254 op_sel:[0,0,1]
	ds_read_b128 v[82:85], v213 offset:51200
	ds_read_b128 v[86:89], v214 offset:51200
	s_waitcnt lgkmcnt(2)
	v_mfma_scale_f32_32x32x64_f8f6f4 v[98:113], v[222:229], v[146:153], v[230:245], v194, v193 op_sel_hi:[0,0,0]
	ds_read_b128 v[222:225], v213 offset:55296
	ds_read_b128 v[226:229], v214 offset:55296
	v_exp_f32_e32 v0, v90
	v_exp_f32_e32 v177, v91
	v_exp_f32_e32 v179, v92
	v_exp_f32_e32 v254, v93
	v_add_f32_e32 v219, v0, v219
	v_add_f32_e32 v219, v177, v219
	v_cvt_pk_fp8_f32 v248, v0, v177
	v_add_f32_e32 v219, v179, v219
	v_add_f32_e32 v219, v254, v219
	v_cvt_pk_fp8_f32 v248, v179, v254 op_sel:[0,0,1]
	v_exp_f32_e32 v0, v94
	v_exp_f32_e32 v177, v95
	v_exp_f32_e32 v179, v96
	v_exp_f32_e32 v254, v97
	v_add_f32_e32 v219, v0, v219
	v_add_f32_e32 v219, v177, v219
	v_cvt_pk_fp8_f32 v249, v0, v177
	v_add_f32_e32 v219, v179, v219
	v_add_f32_e32 v219, v254, v219
	v_cvt_pk_fp8_f32 v249, v179, v254 op_sel:[0,0,1]
	ds_read_b128 v[90:93], v185 offset:59392
	ds_read_b128 v[94:97], v186 offset:59392
	s_waitcnt lgkmcnt(4)
	v_mfma_scale_f32_32x32x64_f8f6f4 v[114:129], v[82:89], v[138:145], v[114:129], v194, v193 op_sel_hi:[0,0,0]
	v_exp_f32_e32 v0, v66
	v_exp_f32_e32 v177, v67
	v_exp_f32_e32 v179, v68
	v_exp_f32_e32 v254, v69
	v_add_f32_e32 v219, v0, v219
	v_add_f32_e32 v219, v177, v219
	v_cvt_pk_fp8_f32 v250, v0, v177
	v_add_f32_e32 v219, v179, v219
	v_add_f32_e32 v219, v254, v219
	v_cvt_pk_fp8_f32 v250, v179, v254 op_sel:[0,0,1]
	s_waitcnt lgkmcnt(2)
	v_mfma_scale_f32_32x32x64_f8f6f4 v[98:113], v[222:229], v[138:145], v[98:113], v194, v193 op_sel_hi:[0,0,0]
	ds_read_b128 v[222:225], v185 offset:61440
	ds_read_b128 v[226:229], v186 offset:61440
	v_exp_f32_e32 v0, v70
	v_exp_f32_e32 v177, v71
	v_exp_f32_e32 v179, v72
	v_exp_f32_e32 v254, v73
	v_add_f32_e32 v219, v0, v219
	v_add_f32_e32 v219, v177, v219
	v_cvt_pk_fp8_f32 v251, v0, v177
	v_add_f32_e32 v219, v179, v219
	v_add_f32_e32 v219, v254, v219
	v_cvt_pk_fp8_f32 v251, v179, v254 op_sel:[0,0,1]
	v_exp_f32_e32 v0, v74
	v_exp_f32_e32 v177, v75
	v_exp_f32_e32 v179, v76
	v_exp_f32_e32 v254, v77
	v_add_f32_e32 v219, v0, v219
	v_add_f32_e32 v219, v177, v219
	v_cvt_pk_fp8_f32 v252, v0, v177
	v_add_f32_e32 v219, v179, v219
	v_add_f32_e32 v219, v254, v219
	v_cvt_pk_fp8_f32 v252, v179, v254 op_sel:[0,0,1]
	s_waitcnt lgkmcnt(2)
	v_mfma_scale_f32_32x32x64_f8f6f4 v[114:129], v[90:97], v[130:137], v[114:129], v194, v193 op_sel_hi:[0,0,0]
	v_exp_f32_e32 v0, v78
	v_exp_f32_e32 v177, v79
	v_exp_f32_e32 v179, v80
	v_exp_f32_e32 v254, v81
	v_add_f32_e32 v219, v0, v219
	v_add_f32_e32 v219, v177, v219
	v_cvt_pk_fp8_f32 v253, v0, v177
	v_add_f32_e32 v219, v179, v219
	v_add_f32_e32 v219, v254, v219
	v_cvt_pk_fp8_f32 v253, v179, v254 op_sel:[0,0,1]
	ds_read_b128 v[90:93], v185 offset:8192
	ds_read_b128 v[94:97], v186 offset:8192
	ds_read_b128 v[82:85], v185 offset:10240
	ds_read_b128 v[86:89], v186 offset:10240
	ds_read_b128 v[74:77], v185 offset:12288
	ds_read_b128 v[78:81], v186 offset:12288
	ds_read_b128 v[66:69], v185 offset:14336
	ds_read_b128 v[70:73], v186 offset:14336
	s_waitcnt lgkmcnt(8)
	v_mfma_scale_f32_32x32x64_f8f6f4 v[98:113], v[222:229], v[130:137], v[98:113], v194, v193 op_sel_hi:[0,0,0]
	v_mov_b32_e32 v0, v219
	s_nop 1
	v_permlane32_swap_b32_e32 v219, v0
	v_add_f32_e32 v219, v219, v0
	v_fma_f32 v209, v209, v218, v219
	v_max_f32_e32 v177, v114, v115
	v_max3_f32 v177, v177, v116, v117
	v_max3_f32 v177, v177, v118, v119
	v_max3_f32 v177, v177, v120, v121
	v_max3_f32 v177, v177, v122, v123
	v_max3_f32 v177, v177, v124, v125
	v_max3_f32 v177, v177, v126, v127
	v_max3_f32 v177, v177, v128, v129
	s_waitcnt lgkmcnt(6)
	v_mfma_scale_f32_32x32x64_f8f6f4 v[50:65], v[246:253], v[90:97], v[50:65], v194, v194 op_sel_hi:[0,0,0]
	s_waitcnt vmcnt(0)
	ds_write_b128 v210, v[158:161]
	ds_write_b128 v211, v[162:165] offset:16384
	ds_write_b128 v212, v[154:157] offset:32768
	s_waitcnt lgkmcnt(7)
	v_mfma_scale_f32_32x32x64_f8f6f4 v[34:49], v[246:253], v[82:89], v[34:49], v194, v194 op_sel_hi:[0,0,0]
	s_waitcnt lgkmcnt(0)
	s_barrier
	s_waitcnt lgkmcnt(2)
	v_mfma_scale_f32_32x32x64_f8f6f4 v[18:33], v[246:253], v[74:81], v[18:33], v194, v194 op_sel_hi:[0,0,0]
	s_waitcnt lgkmcnt(0)
	v_mfma_scale_f32_32x32x64_f8f6f4 v[2:17], v[246:253], v[66:73], v[2:17], v194, v194 op_sel_hi:[0,0,0]
	v_max_f32_e32 v0, v98, v99
	v_max3_f32 v0, v0, v100, v101
	v_max3_f32 v0, v0, v102, v103
	v_max3_f32 v0, v0, v104, v105
	v_max3_f32 v0, v0, v106, v107
	v_max3_f32 v0, v0, v108, v109
	v_max3_f32 v0, v0, v110, v111
	v_max3_f32 v0, v0, v112, v113
	v_max_f32_e32 v177, v177, v0
	v_mov_b32_e32 v0, v177
	v_mov_b32_e32 v221, 1.0
	s_nop 0
	v_permlane32_swap_b32_e32 v177, v0
	v_max_f32_e32 v177, v177, v0
	v_cmp_ge_f32_e32 vcc, s90, v177
	s_cmp_eq_u64 vcc, exec
	s_cbranch_scc0 .Lmla_h4_newmax
; __device__ __forceinline__ void finishSM9(f32x16& p0, f32x16& p1, float alpha, float& l_reg, v8i32& p8) {
; #pragma unroll
;   for (int r = 0; r < 16; ++r) { p0[r] = __builtin_amdgcn_exp2f(p0[r]); p1[r] = __builtin_amdgcn_exp2f(p1[r]); }
;   float ps = 0;
; #pragma unroll
;   for (int r = 0; r < 16; ++r) ps += p0[r];
; #pragma unroll
;   for (int r = 0; r < 16; ++r) ps += p1[r];
;   { auto rr = __builtin_amdgcn_permlane32_swap(__float_as_uint(ps), __float_as_uint(ps), false, false);
;     ps = __uint_as_float(rr[0]) + __uint_as_float(rr[1]); }
;   l_reg = l_reg * alpha + ps;
; #pragma unroll
;   for (int g = 0; g < 4; ++g) {
;     int w = __builtin_amdgcn_cvt_pk_fp8_f32(p0[4 * g], p0[4 * g + 1], 0, false); p8[g] = __builtin_amdgcn_cvt_pk_fp8_f32(p0[4 * g + 2], p0[4 * g + 3], w, true);
;     int u = __builtin_amdgcn_cvt_pk_fp8_f32(p1[4 * g], p1[4 * g + 1], 0, false); p8[4 + g] = __builtin_amdgcn_cvt_pk_fp8_f32(p1[4 * g + 2], p1[4 * g + 3], u, true); }
; }
; __device__ __forceinline__ void pv8(f32x16* o, const char* Vt, const v8i32 p8, int r32, int hi) {
;   const int sw = (r32 >> 2) & 3, a0 = r32 * 64 + (((hi * 2) ^ sw) << 4), a1 = r32 * 64 + (((hi * 2 + 1) ^ sw) << 4);
; #pragma unroll
;   for (int d0 = 0; d0 < 4; ++d0) {
;     const v8i32 vf = cat8(*reinterpret_cast<const v4i32*>(Vt + d0 * 2048 + a0), *reinterpret_cast<const v4i32*>(Vt + d0 * 2048 + a1));
;     o[d0] = __builtin_amdgcn_mfma_scale_f32_32x32x64_f8f6f4(p8, vf, o[d0], 0, 0, 0, 127, 0, 127); }
; }
; __device__ __forceinline__ void qkt9(f32x16& p0, f32x16& p1, const char* Kn, const char* Kr, const v8i32* qf, const float init, int r32, int hi) {
; #pragma unroll
;   for (int r = 0; r < 16; ++r) { p0[r] = init; p1[r] = init; }
; #pragma unroll
;   for (int s = 0; s < 2; ++s) { const int c0 = s * 4 + hi * 2;
;     const v8i32 a0 = cat8(*reinterpret_cast<const v4i32*>(Kn + KN8SW(r32, c0)), *reinterpret_cast<const v4i32*>(Kn + KN8SW(r32, c0 + 1)));
;     const v8i32 a1 = cat8(*reinterpret_cast<const v4i32*>(Kn + 4096 + KN8SW(r32, c0)), *reinterpret_cast<const v4i32*>(Kn + 4096 + KN8SW(r32, c0 + 1)));
;     p0 = __builtin_amdgcn_mfma_scale_f32_32x32x64_f8f6f4(a0, qf[s], p0, 0, 0, 0, 127, 0, 124);
;     p1 = __builtin_amdgcn_mfma_scale_f32_32x32x64_f8f6f4(a1, qf[s], p1, 0, 0, 0, 127, 0, 124); }
;   { const int c0 = hi * 2;
.Lmla_h4_cont:
	ds_read_b128 v[82:85], v215 offset:16384
	ds_read_b128 v[86:89], v216 offset:16384
	ds_read_b128 v[222:225], v215 offset:20480
	ds_read_b128 v[226:229], v216 offset:20480
	global_load_dwordx4 v[158:161], v176, s[18:19]
	global_load_dwordx4 v[162:165], v178, s[16:17]
	global_load_dwordx4 v[154:157], v[180:181], off
	v_add_u32_e32 v176, 0x2000, v176
	v_add_u32_e32 v178, 0x20000, v178
	s_mov_b64 s[20:21], 0x1000
	v_lshl_add_u64 v[180:181], v[180:181], 0, s[20:21]
	v_exp_f32_e32 v0, v114
	v_exp_f32_e32 v177, v115
	v_exp_f32_e32 v179, v116
	v_exp_f32_e32 v254, v117
	v_add_f32_e32 v219, v0, v177
	v_cvt_pk_fp8_f32 v246, v0, v177
	v_add_f32_e32 v219, v179, v219
	v_add_f32_e32 v219, v254, v219
	v_cvt_pk_fp8_f32 v246, v179, v254 op_sel:[0,0,1]
	s_waitcnt lgkmcnt(2)
	v_mfma_scale_f32_32x32x64_f8f6f4 v[82:97], v[82:89], v[146:153], v[230:245], v194, v193 op_sel_hi:[0,0,0]
	v_exp_f32_e32 v0, v118
	v_exp_f32_e32 v177, v119
	v_exp_f32_e32 v179, v120
	v_exp_f32_e32 v254, v121
	v_add_f32_e32 v219, v0, v219
	v_add_f32_e32 v219, v177, v219
	v_cvt_pk_fp8_f32 v247, v0, v177
	v_add_f32_e32 v219, v179, v219
	v_add_f32_e32 v219, v254, v219
	v_cvt_pk_fp8_f32 v247, v179, v254 op_sel:[0,0,1]
	ds_read_b128 v[114:117], v213 offset:16384
	ds_read_b128 v[118:121], v214 offset:16384
	s_waitcnt lgkmcnt(2)
	v_mfma_scale_f32_32x32x64_f8f6f4 v[66:81], v[222:229], v[146:153], v[230:245], v194, v193 op_sel_hi:[0,0,0]
	ds_read_b128 v[222:225], v213 offset:20480
	ds_read_b128 v[226:229], v214 offset:20480
	v_exp_f32_e32 v0, v122
	v_exp_f32_e32 v177, v123
	v_exp_f32_e32 v179, v124
	v_exp_f32_e32 v254, v125
	v_add_f32_e32 v219, v0, v219
	v_add_f32_e32 v219, v177, v219
	v_cvt_pk_fp8_f32 v248, v0, v177
	v_add_f32_e32 v219, v179, v219
	v_add_f32_e32 v219, v254, v219
	v_cvt_pk_fp8_f32 v248, v179, v254 op_sel:[0,0,1]
	v_exp_f32_e32 v0, v126
	v_exp_f32_e32 v177, v127
	v_exp_f32_e32 v179, v128
	v_exp_f32_e32 v254, v129
	v_add_f32_e32 v219, v0, v219
	v_add_f32_e32 v219, v177, v219
	v_cvt_pk_fp8_f32 v249, v0, v177
	v_add_f32_e32 v219, v179, v219
	v_add_f32_e32 v219, v254, v219
	v_cvt_pk_fp8_f32 v249, v179, v254 op_sel:[0,0,1]
	ds_read_b128 v[122:125], v185 offset:32768
	ds_read_b128 v[126:129], v186 offset:32768
	s_waitcnt lgkmcnt(4)
	v_mfma_scale_f32_32x32x64_f8f6f4 v[82:97], v[114:121], v[138:145], v[82:97], v194, v193 op_sel_hi:[0,0,0]
	v_exp_f32_e32 v0, v98
	v_exp_f32_e32 v177, v99
	v_exp_f32_e32 v179, v100
	v_exp_f32_e32 v254, v101
	v_add_f32_e32 v219, v0, v219
	v_add_f32_e32 v219, v177, v219
	v_cvt_pk_fp8_f32 v250, v0, v177
	v_add_f32_e32 v219, v179, v219
	v_add_f32_e32 v219, v254, v219
	v_cvt_pk_fp8_f32 v250, v179, v254 op_sel:[0,0,1]
	s_waitcnt lgkmcnt(2)
	v_mfma_scale_f32_32x32x64_f8f6f4 v[66:81], v[222:229], v[138:145], v[66:81], v194, v193 op_sel_hi:[0,0,0]
	ds_read_b128 v[222:225], v185 offset:34816
	ds_read_b128 v[226:229], v186 offset:34816
	v_exp_f32_e32 v0, v102
	v_exp_f32_e32 v177, v103
	v_exp_f32_e32 v179, v104
	v_exp_f32_e32 v254, v105
	v_add_f32_e32 v219, v0, v219
	v_add_f32_e32 v219, v177, v219
	v_cvt_pk_fp8_f32 v251, v0, v177
	v_add_f32_e32 v219, v179, v219
	v_add_f32_e32 v219, v254, v219
	v_cvt_pk_fp8_f32 v251, v179, v254 op_sel:[0,0,1]
	v_exp_f32_e32 v0, v106
	v_exp_f32_e32 v177, v107
	v_exp_f32_e32 v179, v108
	v_exp_f32_e32 v254, v109
	v_add_f32_e32 v219, v0, v219
	v_add_f32_e32 v219, v177, v219
	v_cvt_pk_fp8_f32 v252, v0, v177
	v_add_f32_e32 v219, v179, v219
	v_add_f32_e32 v219, v254, v219
	v_cvt_pk_fp8_f32 v252, v179, v254 op_sel:[0,0,1]
	s_waitcnt lgkmcnt(2)
	v_mfma_scale_f32_32x32x64_f8f6f4 v[82:97], v[122:129], v[130:137], v[82:97], v194, v193 op_sel_hi:[0,0,0]
	v_exp_f32_e32 v0, v110
	v_exp_f32_e32 v177, v111
	v_exp_f32_e32 v179, v112
	v_exp_f32_e32 v254, v113
	v_add_f32_e32 v219, v0, v219
	v_add_f32_e32 v219, v177, v219
	v_cvt_pk_fp8_f32 v253, v0, v177
	v_add_f32_e32 v219, v179, v219
	v_add_f32_e32 v219, v254, v219
	v_cvt_pk_fp8_f32 v253, v179, v254 op_sel:[0,0,1]
	ds_read_b128 v[122:125], v185 offset:43008
	ds_read_b128 v[126:129], v186 offset:43008
	ds_read_b128 v[114:117], v185 offset:45056
	ds_read_b128 v[118:121], v186 offset:45056
	ds_read_b128 v[106:109], v185 offset:47104
	ds_read_b128 v[110:113], v186 offset:47104
	ds_read_b128 v[98:101], v185 offset:49152
	ds_read_b128 v[102:105], v186 offset:49152
	s_waitcnt lgkmcnt(8)
	v_mfma_scale_f32_32x32x64_f8f6f4 v[66:81], v[222:229], v[130:137], v[66:81], v194, v193 op_sel_hi:[0,0,0]
	v_mov_b32_e32 v0, v219
	s_nop 1
	v_permlane32_swap_b32_e32 v219, v0
	v_add_f32_e32 v219, v219, v0
	v_fma_f32 v209, v209, v221, v219
	v_max_f32_e32 v177, v82, v83
	v_max3_f32 v177, v177, v84, v85
	v_max3_f32 v177, v177, v86, v87
	v_max3_f32 v177, v177, v88, v89
	v_max3_f32 v177, v177, v90, v91
	v_max3_f32 v177, v177, v92, v93
	v_max3_f32 v177, v177, v94, v95
	v_max3_f32 v177, v177, v96, v97
	s_waitcnt lgkmcnt(6)
	v_mfma_scale_f32_32x32x64_f8f6f4 v[50:65], v[246:253], v[122:129], v[50:65], v194, v194 op_sel_hi:[0,0,0]
	s_waitcnt vmcnt(0)
	ds_write_b128 v210, v[158:161] offset:8192
	ds_write_b128 v211, v[162:165] offset:24576
	ds_write_b128 v212, v[154:157] offset:36864
	s_waitcnt lgkmcnt(7)
	v_mfma_scale_f32_32x32x64_f8f6f4 v[34:49], v[246:253], v[114:121], v[34:49], v194, v194 op_sel_hi:[0,0,0]
	s_waitcnt lgkmcnt(0)
	s_barrier
	s_waitcnt lgkmcnt(2)
	v_mfma_scale_f32_32x32x64_f8f6f4 v[18:33], v[246:253], v[106:113], v[18:33], v194, v194 op_sel_hi:[0,0,0]
	s_waitcnt lgkmcnt(0)
	v_mfma_scale_f32_32x32x64_f8f6f4 v[2:17], v[246:253], v[98:105], v[2:17], v194, v194 op_sel_hi:[0,0,0]
	v_max_f32_e32 v0, v66, v67
	v_max3_f32 v0, v0, v68, v69
	v_max3_f32 v0, v0, v70, v71
	v_max3_f32 v0, v0, v72, v73
	v_max3_f32 v0, v0, v74, v75
	v_max3_f32 v0, v0, v76, v77
	v_max3_f32 v0, v0, v78, v79
	v_max3_f32 v0, v0, v80, v81
	v_max_f32_e32 v177, v177, v0
	v_mov_b32_e32 v0, v177
	v_mov_b32_e32 v218, 1.0
	s_nop 0
	v_permlane32_swap_b32_e32 v177, v0
	v_max_f32_e32 v177, v177, v0
	v_cmp_ge_f32_e32 vcc, s90, v177
	s_cmp_eq_u64 vcc, exec
	s_cbranch_scc0 .Lmla_h5_newmax
; __device__ __forceinline__ void finishSM9(f32x16& p0, f32x16& p1, float alpha, float& l_reg, v8i32& p8) {
; #pragma unroll
;   for (int r = 0; r < 16; ++r) { p0[r] = __builtin_amdgcn_exp2f(p0[r]); p1[r] = __builtin_amdgcn_exp2f(p1[r]); }
;   float ps = 0;
; #pragma unroll
;   for (int r = 0; r < 16; ++r) ps += p0[r];
; #pragma unroll
;   for (int r = 0; r < 16; ++r) ps += p1[r];
;   { auto rr = __builtin_amdgcn_permlane32_swap(__float_as_uint(ps), __float_as_uint(ps), false, false);
;     ps = __uint_as_float(rr[0]) + __uint_as_float(rr[1]); }
;   l_reg = l_reg * alpha + ps;
; #pragma unroll
;   for (int g = 0; g < 4; ++g) {
;     int w = __builtin_amdgcn_cvt_pk_fp8_f32(p0[4 * g], p0[4 * g + 1], 0, false); p8[g] = __builtin_amdgcn_cvt_pk_fp8_f32(p0[4 * g + 2], p0[4 * g + 3], w, true);
;     int u = __builtin_amdgcn_cvt_pk_fp8_f32(p1[4 * g], p1[4 * g + 1], 0, false); p8[4 + g] = __builtin_amdgcn_cvt_pk_fp8_f32(p1[4 * g + 2], p1[4 * g + 3], u, true); }
; }
; __device__ __forceinline__ void pv8(f32x16* o, const char* Vt, const v8i32 p8, int r32, int hi) {
;   const int sw = (r32 >> 2) & 3, a0 = r32 * 64 + (((hi * 2) ^ sw) << 4), a1 = r32 * 64 + (((hi * 2 + 1) ^ sw) << 4);
; #pragma unroll
;   for (int d0 = 0; d0 < 4; ++d0) {
;     const v8i32 vf = cat8(*reinterpret_cast<const v4i32*>(Vt + d0 * 2048 + a0), *reinterpret_cast<const v4i32*>(Vt + d0 * 2048 + a1));
;     o[d0] = __builtin_amdgcn_mfma_scale_f32_32x32x64_f8f6f4(p8, vf, o[d0], 0, 0, 0, 127, 0, 127); }
; }
; __device__ __forceinline__ void qkt9(f32x16& p0, f32x16& p1, const char* Kn, const char* Kr, const v8i32* qf, const float init, int r32, int hi) {
; #pragma unroll
;   for (int r = 0; r < 16; ++r) { p0[r] = init; p1[r] = init; }
; #pragma unroll
;   for (int s = 0; s < 2; ++s) { const int c0 = s * 4 + hi * 2;
;     const v8i32 a0 = cat8(*reinterpret_cast<const v4i32*>(Kn + KN8SW(r32, c0)), *reinterpret_cast<const v4i32*>(Kn + KN8SW(r32, c0 + 1)));
;     const v8i32 a1 = cat8(*reinterpret_cast<const v4i32*>(Kn + 4096 + KN8SW(r32, c0)), *reinterpret_cast<const v4i32*>(Kn + 4096 + KN8SW(r32, c0 + 1)));
;     p0 = __builtin_amdgcn_mfma_scale_f32_32x32x64_f8f6f4(a0, qf[s], p0, 0, 0, 0, 127, 0, 124);
;     p1 = __builtin_amdgcn_mfma_scale_f32_32x32x64_f8f6f4(a1, qf[s], p1, 0, 0, 0, 127, 0, 124); }
;   { const int c0 = hi * 2;
.Lmla_h5_cont:
	s_add_i32 s30, s30, 1
	s_cmpk_lt_u32 s30, 42
	s_cbranch_scc1 .LBB0_1321
	ds_read_b128 v[114:117], v215 offset:24576
	ds_read_b128 v[118:121], v216 offset:24576
	ds_read_b128 v[222:225], v215 offset:28672
	ds_read_b128 v[226:229], v216 offset:28672
	global_load_dwordx4 v[158:161], v176, s[18:19]
	global_load_dwordx4 v[162:165], v178, s[16:17]
	global_load_dwordx4 v[154:157], v[180:181], off
	v_add_u32_e32 v176, 0x2000, v176
	v_add_u32_e32 v178, 0x20000, v178
	s_mov_b64 s[20:21], 0x1000
	v_lshl_add_u64 v[180:181], v[180:181], 0, s[20:21]
	v_exp_f32_e32 v0, v82
	v_exp_f32_e32 v177, v83
	v_exp_f32_e32 v179, v84
	v_exp_f32_e32 v254, v85
	v_add_f32_e32 v219, v0, v177
	v_cvt_pk_fp8_f32 v246, v0, v177
	v_add_f32_e32 v219, v179, v219
	v_add_f32_e32 v219, v254, v219
	v_cvt_pk_fp8_f32 v246, v179, v254 op_sel:[0,0,1]
	s_waitcnt lgkmcnt(2)
	v_mfma_scale_f32_32x32x64_f8f6f4 v[114:129], v[114:121], v[146:153], v[230:245], v194, v193 op_sel_hi:[0,0,0]
	v_exp_f32_e32 v0, v86
	v_exp_f32_e32 v177, v87
	v_exp_f32_e32 v179, v88
	v_exp_f32_e32 v254, v89
	v_add_f32_e32 v219, v0, v219
	v_add_f32_e32 v219, v177, v219
	v_cvt_pk_fp8_f32 v247, v0, v177
	v_add_f32_e32 v219, v179, v219
	v_add_f32_e32 v219, v254, v219
	v_cvt_pk_fp8_f32 v247, v179, v254 op_sel:[0,0,1]
	ds_read_b128 v[82:85], v213 offset:24576
	ds_read_b128 v[86:89], v214 offset:24576
	s_waitcnt lgkmcnt(2)
	v_mfma_scale_f32_32x32x64_f8f6f4 v[98:113], v[222:229], v[146:153], v[230:245], v194, v193 op_sel_hi:[0,0,0]
	ds_read_b128 v[222:225], v213 offset:28672
	ds_read_b128 v[226:229], v214 offset:28672
	v_exp_f32_e32 v0, v90
	v_exp_f32_e32 v177, v91
	v_exp_f32_e32 v179, v92
	v_exp_f32_e32 v254, v93
	v_add_f32_e32 v219, v0, v219
	v_add_f32_e32 v219, v177, v219
	v_cvt_pk_fp8_f32 v248, v0, v177
	v_add_f32_e32 v219, v179, v219
	v_add_f32_e32 v219, v254, v219
	v_cvt_pk_fp8_f32 v248, v179, v254 op_sel:[0,0,1]
	v_exp_f32_e32 v0, v94
	v_exp_f32_e32 v177, v95
	v_exp_f32_e32 v179, v96
	v_exp_f32_e32 v254, v97
	v_add_f32_e32 v219, v0, v219
	v_add_f32_e32 v219, v177, v219
	v_cvt_pk_fp8_f32 v249, v0, v177
	v_add_f32_e32 v219, v179, v219
	v_add_f32_e32 v219, v254, v219
	v_cvt_pk_fp8_f32 v249, v179, v254 op_sel:[0,0,1]
	ds_read_b128 v[90:93], v185 offset:36864
	ds_read_b128 v[94:97], v186 offset:36864
	s_waitcnt lgkmcnt(4)
	v_mfma_scale_f32_32x32x64_f8f6f4 v[114:129], v[82:89], v[138:145], v[114:129], v194, v193 op_sel_hi:[0,0,0]
	v_exp_f32_e32 v0, v66
	v_exp_f32_e32 v177, v67
	v_exp_f32_e32 v179, v68
	v_exp_f32_e32 v254, v69
	v_add_f32_e32 v219, v0, v219
	v_add_f32_e32 v219, v177, v219
	v_cvt_pk_fp8_f32 v250, v0, v177
	v_add_f32_e32 v219, v179, v219
	v_add_f32_e32 v219, v254, v219
	v_cvt_pk_fp8_f32 v250, v179, v254 op_sel:[0,0,1]
	s_waitcnt lgkmcnt(2)
	v_mfma_scale_f32_32x32x64_f8f6f4 v[98:113], v[222:229], v[138:145], v[98:113], v194, v193 op_sel_hi:[0,0,0]
	ds_read_b128 v[222:225], v185 offset:38912
	ds_read_b128 v[226:229], v186 offset:38912
	v_exp_f32_e32 v0, v70
	v_exp_f32_e32 v177, v71
	v_exp_f32_e32 v179, v72
	v_exp_f32_e32 v254, v73
	v_add_f32_e32 v219, v0, v219
	v_add_f32_e32 v219, v177, v219
	v_cvt_pk_fp8_f32 v251, v0, v177
	v_add_f32_e32 v219, v179, v219
	v_add_f32_e32 v219, v254, v219
	v_cvt_pk_fp8_f32 v251, v179, v254 op_sel:[0,0,1]
	v_exp_f32_e32 v0, v74
	v_exp_f32_e32 v177, v75
	v_exp_f32_e32 v179, v76
	v_exp_f32_e32 v254, v77
	v_add_f32_e32 v219, v0, v219
	v_add_f32_e32 v219, v177, v219
	v_cvt_pk_fp8_f32 v252, v0, v177
	v_add_f32_e32 v219, v179, v219
	v_add_f32_e32 v219, v254, v219
	v_cvt_pk_fp8_f32 v252, v179, v254 op_sel:[0,0,1]
	s_waitcnt lgkmcnt(2)
	v_mfma_scale_f32_32x32x64_f8f6f4 v[114:129], v[90:97], v[130:137], v[114:129], v194, v193 op_sel_hi:[0,0,0]
	v_exp_f32_e32 v0, v78
	v_exp_f32_e32 v177, v79
	v_exp_f32_e32 v179, v80
	v_exp_f32_e32 v254, v81
	v_add_f32_e32 v219, v0, v219
	v_add_f32_e32 v219, v177, v219
	v_cvt_pk_fp8_f32 v253, v0, v177
	v_add_f32_e32 v219, v179, v219
	v_add_f32_e32 v219, v254, v219
	v_cvt_pk_fp8_f32 v253, v179, v254 op_sel:[0,0,1]
	ds_read_b128 v[90:93], v185 offset:0
	ds_read_b128 v[94:97], v186 offset:0
	ds_read_b128 v[82:85], v185 offset:2048
	ds_read_b128 v[86:89], v186 offset:2048
	ds_read_b128 v[74:77], v185 offset:4096
	ds_read_b128 v[78:81], v186 offset:4096
	ds_read_b128 v[66:69], v185 offset:6144
	ds_read_b128 v[70:73], v186 offset:6144
	s_waitcnt lgkmcnt(8)
	v_mfma_scale_f32_32x32x64_f8f6f4 v[98:113], v[222:229], v[130:137], v[98:113], v194, v193 op_sel_hi:[0,0,0]
	v_mov_b32_e32 v0, v219
	s_nop 1
	v_permlane32_swap_b32_e32 v219, v0
	v_add_f32_e32 v219, v219, v0
	v_fma_f32 v209, v209, v218, v219
	v_max_f32_e32 v177, v114, v115
	v_max3_f32 v177, v177, v116, v117
	v_max3_f32 v177, v177, v118, v119
	v_max3_f32 v177, v177, v120, v121
	v_max3_f32 v177, v177, v122, v123
	v_max3_f32 v177, v177, v124, v125
	v_max3_f32 v177, v177, v126, v127
	v_max3_f32 v177, v177, v128, v129
	s_waitcnt lgkmcnt(6)
	v_mfma_scale_f32_32x32x64_f8f6f4 v[50:65], v[246:253], v[90:97], v[50:65], v194, v194 op_sel_hi:[0,0,0]
	s_waitcnt vmcnt(0)
	ds_write_b128 v210, v[158:161] offset:43008
	ds_write_b128 v211, v[162:165] offset:51200
	ds_write_b128 v212, v[154:157] offset:59392
	s_waitcnt lgkmcnt(7)
	v_mfma_scale_f32_32x32x64_f8f6f4 v[34:49], v[246:253], v[82:89], v[34:49], v194, v194 op_sel_hi:[0,0,0]
	s_waitcnt lgkmcnt(0)
	s_barrier
	s_waitcnt lgkmcnt(2)
	v_mfma_scale_f32_32x32x64_f8f6f4 v[18:33], v[246:253], v[74:81], v[18:33], v194, v194 op_sel_hi:[0,0,0]
	s_waitcnt lgkmcnt(0)
	v_mfma_scale_f32_32x32x64_f8f6f4 v[2:17], v[246:253], v[66:73], v[2:17], v194, v194 op_sel_hi:[0,0,0]
	v_max_f32_e32 v0, v98, v99
	v_max3_f32 v0, v0, v100, v101
	v_max3_f32 v0, v0, v102, v103
	v_max3_f32 v0, v0, v104, v105
	v_max3_f32 v0, v0, v106, v107
	v_max3_f32 v0, v0, v108, v109
	v_max3_f32 v0, v0, v110, v111
	v_max3_f32 v0, v0, v112, v113
	v_max_f32_e32 v177, v177, v0
	v_mov_b32_e32 v0, v177
	v_mov_b32_e32 v221, 1.0
	s_nop 0
	v_permlane32_swap_b32_e32 v177, v0
	v_max_f32_e32 v177, v177, v0
	v_cmp_ge_f32_e32 vcc, s90, v177
	s_cmp_eq_u64 vcc, exec
	s_cbranch_scc0 .Lmla_p0_newmax

; __device__ __forceinline__ void finishSM9(f32x16& p0, f32x16& p1, float alpha, float& l_reg, v8i32& p8) {
; #pragma unroll
;   for (int r = 0; r < 16; ++r) { p0[r] = __builtin_amdgcn_exp2f(p0[r]); p1[r] = __builtin_amdgcn_exp2f(p1[r]); }
;   float ps = 0;
; #pragma unroll
;   for (int r = 0; r < 16; ++r) ps += p0[r];
; #pragma unroll
;   for (int r = 0; r < 16; ++r) ps += p1[r];
;   { auto rr = __builtin_amdgcn_permlane32_swap(__float_as_uint(ps), __float_as_uint(ps), false, false);
;     ps = __uint_as_float(rr[0]) + __uint_as_float(rr[1]); }
;   l_reg = l_reg * alpha + ps;
; #pragma unroll
;   for (int g = 0; g < 4; ++g) {
;     int w = __builtin_amdgcn_cvt_pk_fp8_f32(p0[4 * g], p0[4 * g + 1], 0, false); p8[g] = __builtin_amdgcn_cvt_pk_fp8_f32(p0[4 * g + 2], p0[4 * g + 3], w, true);
;     int u = __builtin_amdgcn_cvt_pk_fp8_f32(p1[4 * g], p1[4 * g + 1], 0, false); p8[4 + g] = __builtin_amdgcn_cvt_pk_fp8_f32(p1[4 * g + 2], p1[4 * g + 3], u, true); }
; }
; __device__ __forceinline__ void pv8(f32x16* o, const char* Vt, const v8i32 p8, int r32, int hi) {
;   const int sw = (r32 >> 2) & 3, a0 = r32 * 64 + (((hi * 2) ^ sw) << 4), a1 = r32 * 64 + (((hi * 2 + 1) ^ sw) << 4);
; #pragma unroll
;   for (int d0 = 0; d0 < 4; ++d0) {
;     const v8i32 vf = cat8(*reinterpret_cast<const v4i32*>(Vt + d0 * 2048 + a0), *reinterpret_cast<const v4i32*>(Vt + d0 * 2048 + a1));
;     o[d0] = __builtin_amdgcn_mfma_scale_f32_32x32x64_f8f6f4(p8, vf, o[d0], 0, 0, 0, 127, 0, 127); }
; }
; __device__ __forceinline__ void qkt9(f32x16& p0, f32x16& p1, const char* Kn, const char* Kr, const v8i32* qf, const float init, int r32, int hi) {
; #pragma unroll
;   for (int r = 0; r < 16; ++r) { p0[r] = init; p1[r] = init; }
; #pragma unroll
;   for (int s = 0; s < 2; ++s) { const int c0 = s * 4 + hi * 2;
;     const v8i32 a0 = cat8(*reinterpret_cast<const v4i32*>(Kn + KN8SW(r32, c0)), *reinterpret_cast<const v4i32*>(Kn + KN8SW(r32, c0 + 1)));
;     const v8i32 a1 = cat8(*reinterpret_cast<const v4i32*>(Kn + 4096 + KN8SW(r32, c0)), *reinterpret_cast<const v4i32*>(Kn + 4096 + KN8SW(r32, c0 + 1)));
;     p0 = __builtin_amdgcn_mfma_scale_f32_32x32x64_f8f6f4(a0, qf[s], p0, 0, 0, 0, 127, 0, 124);
;     p1 = __builtin_amdgcn_mfma_scale_f32_32x32x64_f8f6f4(a1, qf[s], p1, 0, 0, 0, 127, 0, 124); }
;   { const int c0 = hi * 2;
.Lmla_stag_loop:
	ds_read_b128 v[114:117], v215 offset:24576
	ds_read_b128 v[118:121], v216 offset:24576
	ds_read_b128 v[222:225], v215 offset:28672
	ds_read_b128 v[226:229], v216 offset:28672
	v_exp_f32_e32 v0, v82
	v_exp_f32_e32 v177, v83
	v_exp_f32_e32 v179, v84
	v_exp_f32_e32 v254, v85
	v_add_f32_e32 v219, v0, v177
	v_cvt_pk_fp8_f32 v246, v0, v177
	v_add_f32_e32 v219, v179, v219
	v_add_f32_e32 v219, v254, v219
	v_cvt_pk_fp8_f32 v246, v179, v254 op_sel:[0,0,1]
	s_waitcnt lgkmcnt(2)
	v_mfma_scale_f32_32x32x64_f8f6f4 v[114:129], v[114:121], v[146:153], v[230:245], v194, v193 op_sel_hi:[0,0,0]
	v_exp_f32_e32 v0, v86
	v_exp_f32_e32 v177, v87
	v_exp_f32_e32 v179, v88
	v_exp_f32_e32 v254, v89
	v_add_f32_e32 v219, v0, v219
	v_add_f32_e32 v219, v177, v219
	v_cvt_pk_fp8_f32 v247, v0, v177
	v_add_f32_e32 v219, v179, v219
	v_add_f32_e32 v219, v254, v219
	v_cvt_pk_fp8_f32 v247, v179, v254 op_sel:[0,0,1]
	ds_read_b128 v[82:85], v213 offset:24576
	ds_read_b128 v[86:89], v214 offset:24576
	s_waitcnt lgkmcnt(2)
	v_mfma_scale_f32_32x32x64_f8f6f4 v[98:113], v[222:229], v[146:153], v[230:245], v194, v193 op_sel_hi:[0,0,0]
	ds_read_b128 v[222:225], v213 offset:28672
	ds_read_b128 v[226:229], v214 offset:28672
	v_exp_f32_e32 v0, v90
	v_exp_f32_e32 v177, v91
	v_exp_f32_e32 v179, v92
	v_exp_f32_e32 v254, v93
	v_add_f32_e32 v219, v0, v219
	v_add_f32_e32 v219, v177, v219
	v_cvt_pk_fp8_f32 v248, v0, v177
	v_add_f32_e32 v219, v179, v219
	v_add_f32_e32 v219, v254, v219
	v_cvt_pk_fp8_f32 v248, v179, v254 op_sel:[0,0,1]
	v_exp_f32_e32 v0, v94
	v_exp_f32_e32 v177, v95
	v_exp_f32_e32 v179, v96
	v_exp_f32_e32 v254, v97
	v_add_f32_e32 v219, v0, v219
	v_add_f32_e32 v219, v177, v219
	v_cvt_pk_fp8_f32 v249, v0, v177
	v_add_f32_e32 v219, v179, v219
	v_add_f32_e32 v219, v254, v219
	v_cvt_pk_fp8_f32 v249, v179, v254 op_sel:[0,0,1]
	ds_read_b128 v[90:93], v185 offset:36864
	ds_read_b128 v[94:97], v186 offset:36864
	s_waitcnt lgkmcnt(4)
	v_mfma_scale_f32_32x32x64_f8f6f4 v[114:129], v[82:89], v[138:145], v[114:129], v194, v193 op_sel_hi:[0,0,0]
	v_exp_f32_e32 v0, v66
	v_exp_f32_e32 v177, v67
	v_exp_f32_e32 v179, v68
	v_exp_f32_e32 v254, v69
	v_add_f32_e32 v219, v0, v219
	v_add_f32_e32 v219, v177, v219
	v_cvt_pk_fp8_f32 v250, v0, v177
	v_add_f32_e32 v219, v179, v219
	v_add_f32_e32 v219, v254, v219
	v_cvt_pk_fp8_f32 v250, v179, v254 op_sel:[0,0,1]
	s_waitcnt lgkmcnt(2)
	v_mfma_scale_f32_32x32x64_f8f6f4 v[98:113], v[222:229], v[138:145], v[98:113], v194, v193 op_sel_hi:[0,0,0]
	ds_read_b128 v[222:225], v185 offset:38912
	ds_read_b128 v[226:229], v186 offset:38912
	v_exp_f32_e32 v0, v70
	v_exp_f32_e32 v177, v71
	v_exp_f32_e32 v179, v72
	v_exp_f32_e32 v254, v73
	v_add_f32_e32 v219, v0, v219
	v_add_f32_e32 v219, v177, v219
	v_cvt_pk_fp8_f32 v251, v0, v177
	v_add_f32_e32 v219, v179, v219
	v_add_f32_e32 v219, v254, v219
	v_cvt_pk_fp8_f32 v251, v179, v254 op_sel:[0,0,1]
	v_exp_f32_e32 v0, v74
	v_exp_f32_e32 v177, v75
	v_exp_f32_e32 v179, v76
	v_exp_f32_e32 v254, v77
	v_add_f32_e32 v219, v0, v219
	v_add_f32_e32 v219, v177, v219
	v_cvt_pk_fp8_f32 v252, v0, v177
	v_add_f32_e32 v219, v179, v219
	v_add_f32_e32 v219, v254, v219
	v_cvt_pk_fp8_f32 v252, v179, v254 op_sel:[0,0,1]
	s_waitcnt lgkmcnt(2)
	v_mfma_scale_f32_32x32x64_f8f6f4 v[114:129], v[90:97], v[130:137], v[114:129], v194, v193 op_sel_hi:[0,0,0]
	v_exp_f32_e32 v0, v78
	v_exp_f32_e32 v177, v79
	v_exp_f32_e32 v179, v80
	v_exp_f32_e32 v254, v81
	v_add_f32_e32 v219, v0, v219
	v_add_f32_e32 v219, v177, v219
	v_cvt_pk_fp8_f32 v253, v0, v177
	v_add_f32_e32 v219, v179, v219
	v_add_f32_e32 v219, v254, v219
	v_cvt_pk_fp8_f32 v253, v179, v254 op_sel:[0,0,1]
	ds_read_b128 v[90:93], v185 offset:0
	ds_read_b128 v[94:97], v186 offset:0
	ds_read_b128 v[82:85], v185 offset:2048
	ds_read_b128 v[86:89], v186 offset:2048
	ds_read_b128 v[74:77], v185 offset:4096
	ds_read_b128 v[78:81], v186 offset:4096
	ds_read_b128 v[66:69], v185 offset:6144
	ds_read_b128 v[70:73], v186 offset:6144
	s_waitcnt vmcnt(0)
	ds_write_b128 v210, v[158:161] offset:43008
	ds_write_b128 v211, v[162:165] offset:51200
	s_waitcnt lgkmcnt(10)
	v_mfma_scale_f32_32x32x64_f8f6f4 v[98:113], v[222:229], v[130:137], v[98:113], v194, v193 op_sel_hi:[0,0,0]
	s_waitcnt lgkmcnt(0)
	s_barrier
	global_load_dwordx4 v[158:161], v176, s[18:19]
	global_load_dwordx4 v[162:165], v178, s[16:17]
	v_add_u32_e32 v176, 0x2000, v176
	v_add_u32_e32 v178, 0x20000, v178
	v_mov_b32_e32 v0, v219
	s_nop 1
	v_permlane32_swap_b32_e32 v219, v0
	v_add_f32_e32 v219, v219, v0
	v_fma_f32 v209, v209, v218, v219
	v_max_f32_e32 v177, v114, v115
	v_max3_f32 v177, v177, v116, v117
	v_max3_f32 v177, v177, v118, v119
	v_max3_f32 v177, v177, v120, v121
	v_max3_f32 v177, v177, v122, v123
	v_max3_f32 v177, v177, v124, v125
	v_max3_f32 v177, v177, v126, v127
	v_max3_f32 v177, v177, v128, v129
	s_waitcnt lgkmcnt(6)
	v_mfma_scale_f32_32x32x64_f8f6f4 v[50:65], v[246:253], v[90:97], v[50:65], v194, v194 op_sel_hi:[0,0,0]
	s_waitcnt lgkmcnt(4)
	v_mfma_scale_f32_32x32x64_f8f6f4 v[34:49], v[246:253], v[82:89], v[34:49], v194, v194 op_sel_hi:[0,0,0]
	s_waitcnt lgkmcnt(2)
	v_mfma_scale_f32_32x32x64_f8f6f4 v[18:33], v[246:253], v[74:81], v[18:33], v194, v194 op_sel_hi:[0,0,0]
	s_waitcnt lgkmcnt(0)
	v_mfma_scale_f32_32x32x64_f8f6f4 v[2:17], v[246:253], v[66:73], v[2:17], v194, v194 op_sel_hi:[0,0,0]
	v_max_f32_e32 v0, v98, v99
	v_max3_f32 v0, v0, v100, v101
	v_max3_f32 v0, v0, v102, v103
	v_max3_f32 v0, v0, v104, v105
	v_max3_f32 v0, v0, v106, v107
	v_max3_f32 v0, v0, v108, v109
	v_max3_f32 v0, v0, v110, v111
	v_max3_f32 v0, v0, v112, v113
	v_max_f32_e32 v177, v177, v0
	v_mov_b32_e32 v0, v177
	v_mov_b32_e32 v221, 1.0
	s_nop 0
	v_permlane32_swap_b32_e32 v177, v0
	v_max_f32_e32 v177, v177, v0
	v_cmp_ge_f32_e32 vcc, s90, v177
	s_cmp_eq_u64 vcc, exec
	s_cbranch_scc0 .Lmla_s0_newmax
; __device__ __forceinline__ void finishSM9(f32x16& p0, f32x16& p1, float alpha, float& l_reg, v8i32& p8) {
; #pragma unroll
;   for (int r = 0; r < 16; ++r) { p0[r] = __builtin_amdgcn_exp2f(p0[r]); p1[r] = __builtin_amdgcn_exp2f(p1[r]); }
;   float ps = 0;
; #pragma unroll
;   for (int r = 0; r < 16; ++r) ps += p0[r];
; #pragma unroll
;   for (int r = 0; r < 16; ++r) ps += p1[r];
;   { auto rr = __builtin_amdgcn_permlane32_swap(__float_as_uint(ps), __float_as_uint(ps), false, false);
;     ps = __uint_as_float(rr[0]) + __uint_as_float(rr[1]); }
;   l_reg = l_reg * alpha + ps;
; #pragma unroll
;   for (int g = 0; g < 4; ++g) {
;     int w = __builtin_amdgcn_cvt_pk_fp8_f32(p0[4 * g], p0[4 * g + 1], 0, false); p8[g] = __builtin_amdgcn_cvt_pk_fp8_f32(p0[4 * g + 2], p0[4 * g + 3], w, true);
;     int u = __builtin_amdgcn_cvt_pk_fp8_f32(p1[4 * g], p1[4 * g + 1], 0, false); p8[4 + g] = __builtin_amdgcn_cvt_pk_fp8_f32(p1[4 * g + 2], p1[4 * g + 3], u, true); }
; }
; __device__ __forceinline__ void pv8(f32x16* o, const char* Vt, const v8i32 p8, int r32, int hi) {
;   const int sw = (r32 >> 2) & 3, a0 = r32 * 64 + (((hi * 2) ^ sw) << 4), a1 = r32 * 64 + (((hi * 2 + 1) ^ sw) << 4);
; #pragma unroll
;   for (int d0 = 0; d0 < 4; ++d0) {
;     const v8i32 vf = cat8(*reinterpret_cast<const v4i32*>(Vt + d0 * 2048 + a0), *reinterpret_cast<const v4i32*>(Vt + d0 * 2048 + a1));
;     o[d0] = __builtin_amdgcn_mfma_scale_f32_32x32x64_f8f6f4(p8, vf, o[d0], 0, 0, 0, 127, 0, 127); }
; }
; __device__ __forceinline__ void qkt9(f32x16& p0, f32x16& p1, const char* Kn, const char* Kr, const v8i32* qf, const float init, int r32, int hi) {
; #pragma unroll
;   for (int r = 0; r < 16; ++r) { p0[r] = init; p1[r] = init; }
; #pragma unroll
;   for (int s = 0; s < 2; ++s) { const int c0 = s * 4 + hi * 2;
;     const v8i32 a0 = cat8(*reinterpret_cast<const v4i32*>(Kn + KN8SW(r32, c0)), *reinterpret_cast<const v4i32*>(Kn + KN8SW(r32, c0 + 1)));
;     const v8i32 a1 = cat8(*reinterpret_cast<const v4i32*>(Kn + 4096 + KN8SW(r32, c0)), *reinterpret_cast<const v4i32*>(Kn + 4096 + KN8SW(r32, c0 + 1)));
;     p0 = __builtin_amdgcn_mfma_scale_f32_32x32x64_f8f6f4(a0, qf[s], p0, 0, 0, 0, 127, 0, 124);
;     p1 = __builtin_amdgcn_mfma_scale_f32_32x32x64_f8f6f4(a1, qf[s], p1, 0, 0, 0, 127, 0, 124); }
;   { const int c0 = hi * 2;
.Lmla_s0_cont:
	ds_read_b128 v[82:85], v215 offset:51200
	ds_read_b128 v[86:89], v216 offset:51200
	ds_read_b128 v[222:225], v215 offset:55296
	ds_read_b128 v[226:229], v216 offset:55296
	v_exp_f32_e32 v0, v114
	v_exp_f32_e32 v177, v115
	v_exp_f32_e32 v179, v116
	v_exp_f32_e32 v254, v117
	v_add_f32_e32 v219, v0, v177
	v_cvt_pk_fp8_f32 v246, v0, v177
	v_add_f32_e32 v219, v179, v219
	v_add_f32_e32 v219, v254, v219
	v_cvt_pk_fp8_f32 v246, v179, v254 op_sel:[0,0,1]
	s_waitcnt lgkmcnt(2)
	v_mfma_scale_f32_32x32x64_f8f6f4 v[82:97], v[82:89], v[146:153], v[230:245], v194, v193 op_sel_hi:[0,0,0]
	v_exp_f32_e32 v0, v118
	v_exp_f32_e32 v177, v119
	v_exp_f32_e32 v179, v120
	v_exp_f32_e32 v254, v121
	v_add_f32_e32 v219, v0, v219
	v_add_f32_e32 v219, v177, v219
	v_cvt_pk_fp8_f32 v247, v0, v177
	v_add_f32_e32 v219, v179, v219
	v_add_f32_e32 v219, v254, v219
	v_cvt_pk_fp8_f32 v247, v179, v254 op_sel:[0,0,1]
	ds_read_b128 v[114:117], v213 offset:51200
	ds_read_b128 v[118:121], v214 offset:51200
	s_waitcnt lgkmcnt(2)
	v_mfma_scale_f32_32x32x64_f8f6f4 v[66:81], v[222:229], v[146:153], v[230:245], v194, v193 op_sel_hi:[0,0,0]
	ds_read_b128 v[222:225], v213 offset:55296
	ds_read_b128 v[226:229], v214 offset:55296
	v_exp_f32_e32 v0, v122
	v_exp_f32_e32 v177, v123
	v_exp_f32_e32 v179, v124
	v_exp_f32_e32 v254, v125
	v_add_f32_e32 v219, v0, v219
	v_add_f32_e32 v219, v177, v219
	v_cvt_pk_fp8_f32 v248, v0, v177
	v_add_f32_e32 v219, v179, v219
	v_add_f32_e32 v219, v254, v219
	v_cvt_pk_fp8_f32 v248, v179, v254 op_sel:[0,0,1]
	v_exp_f32_e32 v0, v126
	v_exp_f32_e32 v177, v127
	v_exp_f32_e32 v179, v128
	v_exp_f32_e32 v254, v129
	v_add_f32_e32 v219, v0, v219
	v_add_f32_e32 v219, v177, v219
	v_cvt_pk_fp8_f32 v249, v0, v177
	v_add_f32_e32 v219, v179, v219
	v_add_f32_e32 v219, v254, v219
	v_cvt_pk_fp8_f32 v249, v179, v254 op_sel:[0,0,1]
	ds_read_b128 v[122:125], v185 offset:59392
	ds_read_b128 v[126:129], v186 offset:59392
	s_waitcnt lgkmcnt(4)
	v_mfma_scale_f32_32x32x64_f8f6f4 v[82:97], v[114:121], v[138:145], v[82:97], v194, v193 op_sel_hi:[0,0,0]
	v_exp_f32_e32 v0, v98
	v_exp_f32_e32 v177, v99
	v_exp_f32_e32 v179, v100
	v_exp_f32_e32 v254, v101
	v_add_f32_e32 v219, v0, v219
	v_add_f32_e32 v219, v177, v219
	v_cvt_pk_fp8_f32 v250, v0, v177
	v_add_f32_e32 v219, v179, v219
	v_add_f32_e32 v219, v254, v219
	v_cvt_pk_fp8_f32 v250, v179, v254 op_sel:[0,0,1]
	s_waitcnt lgkmcnt(2)
	v_mfma_scale_f32_32x32x64_f8f6f4 v[66:81], v[222:229], v[138:145], v[66:81], v194, v193 op_sel_hi:[0,0,0]
	ds_read_b128 v[222:225], v185 offset:61440
	ds_read_b128 v[226:229], v186 offset:61440
	v_exp_f32_e32 v0, v102
	v_exp_f32_e32 v177, v103
	v_exp_f32_e32 v179, v104
	v_exp_f32_e32 v254, v105
	v_add_f32_e32 v219, v0, v219
	v_add_f32_e32 v219, v177, v219
	v_cvt_pk_fp8_f32 v251, v0, v177
	v_add_f32_e32 v219, v179, v219
	v_add_f32_e32 v219, v254, v219
	v_cvt_pk_fp8_f32 v251, v179, v254 op_sel:[0,0,1]
	v_exp_f32_e32 v0, v106
	v_exp_f32_e32 v177, v107
	v_exp_f32_e32 v179, v108
	v_exp_f32_e32 v254, v109
	v_add_f32_e32 v219, v0, v219
	v_add_f32_e32 v219, v177, v219
	v_cvt_pk_fp8_f32 v252, v0, v177
	v_add_f32_e32 v219, v179, v219
	v_add_f32_e32 v219, v254, v219
	v_cvt_pk_fp8_f32 v252, v179, v254 op_sel:[0,0,1]
	s_waitcnt lgkmcnt(2)
	v_mfma_scale_f32_32x32x64_f8f6f4 v[82:97], v[122:129], v[130:137], v[82:97], v194, v193 op_sel_hi:[0,0,0]
	v_exp_f32_e32 v0, v110
	v_exp_f32_e32 v177, v111
	v_exp_f32_e32 v179, v112
	v_exp_f32_e32 v254, v113
	v_add_f32_e32 v219, v0, v219
	v_add_f32_e32 v219, v177, v219
	v_cvt_pk_fp8_f32 v253, v0, v177
	v_add_f32_e32 v219, v179, v219
	v_add_f32_e32 v219, v254, v219
	v_cvt_pk_fp8_f32 v253, v179, v254 op_sel:[0,0,1]
	ds_read_b128 v[122:125], v185 offset:8192
	ds_read_b128 v[126:129], v186 offset:8192
	ds_read_b128 v[114:117], v185 offset:10240
	ds_read_b128 v[118:121], v186 offset:10240
	ds_read_b128 v[106:109], v185 offset:12288
	ds_read_b128 v[110:113], v186 offset:12288
	ds_read_b128 v[98:101], v185 offset:14336
	ds_read_b128 v[102:105], v186 offset:14336
	s_waitcnt vmcnt(0)
	ds_write_b128 v210, v[158:161]
	ds_write_b128 v211, v[162:165] offset:16384
	s_waitcnt lgkmcnt(10)
	v_mfma_scale_f32_32x32x64_f8f6f4 v[66:81], v[222:229], v[130:137], v[66:81], v194, v193 op_sel_hi:[0,0,0]
	s_waitcnt lgkmcnt(0)
	s_barrier
	global_load_dwordx4 v[158:161], v176, s[18:19]
	global_load_dwordx4 v[162:165], v178, s[16:17]
	v_add_u32_e32 v176, 0x2000, v176
	v_add_u32_e32 v178, 0x20000, v178
	v_mov_b32_e32 v0, v219
	s_nop 1
	v_permlane32_swap_b32_e32 v219, v0
	v_add_f32_e32 v219, v219, v0
	v_fma_f32 v209, v209, v221, v219
	v_max_f32_e32 v177, v82, v83
	v_max3_f32 v177, v177, v84, v85
	v_max3_f32 v177, v177, v86, v87
	v_max3_f32 v177, v177, v88, v89
	v_max3_f32 v177, v177, v90, v91
	v_max3_f32 v177, v177, v92, v93
	v_max3_f32 v177, v177, v94, v95
	v_max3_f32 v177, v177, v96, v97
	s_waitcnt lgkmcnt(6)
	v_mfma_scale_f32_32x32x64_f8f6f4 v[50:65], v[246:253], v[122:129], v[50:65], v194, v194 op_sel_hi:[0,0,0]
	s_waitcnt lgkmcnt(4)
	v_mfma_scale_f32_32x32x64_f8f6f4 v[34:49], v[246:253], v[114:121], v[34:49], v194, v194 op_sel_hi:[0,0,0]
	s_waitcnt lgkmcnt(2)
	v_mfma_scale_f32_32x32x64_f8f6f4 v[18:33], v[246:253], v[106:113], v[18:33], v194, v194 op_sel_hi:[0,0,0]
	s_waitcnt lgkmcnt(0)
	v_mfma_scale_f32_32x32x64_f8f6f4 v[2:17], v[246:253], v[98:105], v[2:17], v194, v194 op_sel_hi:[0,0,0]
	v_max_f32_e32 v0, v66, v67
	v_max3_f32 v0, v0, v68, v69
	v_max3_f32 v0, v0, v70, v71
	v_max3_f32 v0, v0, v72, v73
	v_max3_f32 v0, v0, v74, v75
	v_max3_f32 v0, v0, v76, v77
	v_max3_f32 v0, v0, v78, v79
	v_max3_f32 v0, v0, v80, v81
	v_max_f32_e32 v177, v177, v0
	v_mov_b32_e32 v0, v177
	v_mov_b32_e32 v218, 1.0
	s_nop 0
	v_permlane32_swap_b32_e32 v177, v0
	v_max_f32_e32 v177, v177, v0
	v_cmp_ge_f32_e32 vcc, s90, v177
	s_cmp_eq_u64 vcc, exec
	s_cbranch_scc0 .Lmla_s1_newmax
; __device__ __forceinline__ void finishSM9(f32x16& p0, f32x16& p1, float alpha, float& l_reg, v8i32& p8) {
; #pragma unroll
;   for (int r = 0; r < 16; ++r) { p0[r] = __builtin_amdgcn_exp2f(p0[r]); p1[r] = __builtin_amdgcn_exp2f(p1[r]); }
;   float ps = 0;
; #pragma unroll
;   for (int r = 0; r < 16; ++r) ps += p0[r];
; #pragma unroll
;   for (int r = 0; r < 16; ++r) ps += p1[r];
;   { auto rr = __builtin_amdgcn_permlane32_swap(__float_as_uint(ps), __float_as_uint(ps), false, false);
;     ps = __uint_as_float(rr[0]) + __uint_as_float(rr[1]); }
;   l_reg = l_reg * alpha + ps;
; #pragma unroll
;   for (int g = 0; g < 4; ++g) {
;     int w = __builtin_amdgcn_cvt_pk_fp8_f32(p0[4 * g], p0[4 * g + 1], 0, false); p8[g] = __builtin_amdgcn_cvt_pk_fp8_f32(p0[4 * g + 2], p0[4 * g + 3], w, true);
;     int u = __builtin_amdgcn_cvt_pk_fp8_f32(p1[4 * g], p1[4 * g + 1], 0, false); p8[4 + g] = __builtin_amdgcn_cvt_pk_fp8_f32(p1[4 * g + 2], p1[4 * g + 3], u, true); }
; }
; __device__ __forceinline__ void pv8(f32x16* o, const char* Vt, const v8i32 p8, int r32, int hi) {
;   const int sw = (r32 >> 2) & 3, a0 = r32 * 64 + (((hi * 2) ^ sw) << 4), a1 = r32 * 64 + (((hi * 2 + 1) ^ sw) << 4);
; #pragma unroll
;   for (int d0 = 0; d0 < 4; ++d0) {
;     const v8i32 vf = cat8(*reinterpret_cast<const v4i32*>(Vt + d0 * 2048 + a0), *reinterpret_cast<const v4i32*>(Vt + d0 * 2048 + a1));
;     o[d0] = __builtin_amdgcn_mfma_scale_f32_32x32x64_f8f6f4(p8, vf, o[d0], 0, 0, 0, 127, 0, 127); }
; }
; __device__ __forceinline__ void qkt9(f32x16& p0, f32x16& p1, const char* Kn, const char* Kr, const v8i32* qf, const float init, int r32, int hi) {
; #pragma unroll
;   for (int r = 0; r < 16; ++r) { p0[r] = init; p1[r] = init; }
; #pragma unroll
;   for (int s = 0; s < 2; ++s) { const int c0 = s * 4 + hi * 2;
;     const v8i32 a0 = cat8(*reinterpret_cast<const v4i32*>(Kn + KN8SW(r32, c0)), *reinterpret_cast<const v4i32*>(Kn + KN8SW(r32, c0 + 1)));
;     const v8i32 a1 = cat8(*reinterpret_cast<const v4i32*>(Kn + 4096 + KN8SW(r32, c0)), *reinterpret_cast<const v4i32*>(Kn + 4096 + KN8SW(r32, c0 + 1)));
;     p0 = __builtin_amdgcn_mfma_scale_f32_32x32x64_f8f6f4(a0, qf[s], p0, 0, 0, 0, 127, 0, 124);
;     p1 = __builtin_amdgcn_mfma_scale_f32_32x32x64_f8f6f4(a1, qf[s], p1, 0, 0, 0, 127, 0, 124); }
;   { const int c0 = hi * 2;
.Lmla_s1_cont:
	ds_read_b128 v[114:117], v215 offset:16384
	ds_read_b128 v[118:121], v216 offset:16384
	ds_read_b128 v[222:225], v215 offset:20480
	ds_read_b128 v[226:229], v216 offset:20480
	v_exp_f32_e32 v0, v82
	v_exp_f32_e32 v177, v83
	v_exp_f32_e32 v179, v84
	v_exp_f32_e32 v254, v85
	v_add_f32_e32 v219, v0, v177
	v_cvt_pk_fp8_f32 v246, v0, v177
	v_add_f32_e32 v219, v179, v219
	v_add_f32_e32 v219, v254, v219
	v_cvt_pk_fp8_f32 v246, v179, v254 op_sel:[0,0,1]
	s_waitcnt lgkmcnt(2)
	v_mfma_scale_f32_32x32x64_f8f6f4 v[114:129], v[114:121], v[146:153], v[230:245], v194, v193 op_sel_hi:[0,0,0]
	v_exp_f32_e32 v0, v86
	v_exp_f32_e32 v177, v87
	v_exp_f32_e32 v179, v88
	v_exp_f32_e32 v254, v89
	v_add_f32_e32 v219, v0, v219
	v_add_f32_e32 v219, v177, v219
	v_cvt_pk_fp8_f32 v247, v0, v177
	v_add_f32_e32 v219, v179, v219
	v_add_f32_e32 v219, v254, v219
	v_cvt_pk_fp8_f32 v247, v179, v254 op_sel:[0,0,1]
	ds_read_b128 v[82:85], v213 offset:16384
	ds_read_b128 v[86:89], v214 offset:16384
	s_waitcnt lgkmcnt(2)
	v_mfma_scale_f32_32x32x64_f8f6f4 v[98:113], v[222:229], v[146:153], v[230:245], v194, v193 op_sel_hi:[0,0,0]
	ds_read_b128 v[222:225], v213 offset:20480
	ds_read_b128 v[226:229], v214 offset:20480
	v_exp_f32_e32 v0, v90
	v_exp_f32_e32 v177, v91
	v_exp_f32_e32 v179, v92
	v_exp_f32_e32 v254, v93
	v_add_f32_e32 v219, v0, v219
	v_add_f32_e32 v219, v177, v219
	v_cvt_pk_fp8_f32 v248, v0, v177
	v_add_f32_e32 v219, v179, v219
	v_add_f32_e32 v219, v254, v219
	v_cvt_pk_fp8_f32 v248, v179, v254 op_sel:[0,0,1]
	v_exp_f32_e32 v0, v94
	v_exp_f32_e32 v177, v95
	v_exp_f32_e32 v179, v96
	v_exp_f32_e32 v254, v97
	v_add_f32_e32 v219, v0, v219
	v_add_f32_e32 v219, v177, v219
	v_cvt_pk_fp8_f32 v249, v0, v177
	v_add_f32_e32 v219, v179, v219
	v_add_f32_e32 v219, v254, v219
	v_cvt_pk_fp8_f32 v249, v179, v254 op_sel:[0,0,1]
	ds_read_b128 v[90:93], v185 offset:32768
	ds_read_b128 v[94:97], v186 offset:32768
	s_waitcnt lgkmcnt(4)
	v_mfma_scale_f32_32x32x64_f8f6f4 v[114:129], v[82:89], v[138:145], v[114:129], v194, v193 op_sel_hi:[0,0,0]
	v_exp_f32_e32 v0, v66
	v_exp_f32_e32 v177, v67
	v_exp_f32_e32 v179, v68
	v_exp_f32_e32 v254, v69
	v_add_f32_e32 v219, v0, v219
	v_add_f32_e32 v219, v177, v219
	v_cvt_pk_fp8_f32 v250, v0, v177
	v_add_f32_e32 v219, v179, v219
	v_add_f32_e32 v219, v254, v219
	v_cvt_pk_fp8_f32 v250, v179, v254 op_sel:[0,0,1]
	s_waitcnt lgkmcnt(2)
	v_mfma_scale_f32_32x32x64_f8f6f4 v[98:113], v[222:229], v[138:145], v[98:113], v194, v193 op_sel_hi:[0,0,0]
	ds_read_b128 v[222:225], v185 offset:34816
	ds_read_b128 v[226:229], v186 offset:34816
	v_exp_f32_e32 v0, v70
	v_exp_f32_e32 v177, v71
	v_exp_f32_e32 v179, v72
	v_exp_f32_e32 v254, v73
	v_add_f32_e32 v219, v0, v219
	v_add_f32_e32 v219, v177, v219
	v_cvt_pk_fp8_f32 v251, v0, v177
	v_add_f32_e32 v219, v179, v219
	v_add_f32_e32 v219, v254, v219
	v_cvt_pk_fp8_f32 v251, v179, v254 op_sel:[0,0,1]
	v_exp_f32_e32 v0, v74
	v_exp_f32_e32 v177, v75
	v_exp_f32_e32 v179, v76
	v_exp_f32_e32 v254, v77
	v_add_f32_e32 v219, v0, v219
	v_add_f32_e32 v219, v177, v219
	v_cvt_pk_fp8_f32 v252, v0, v177
	v_add_f32_e32 v219, v179, v219
	v_add_f32_e32 v219, v254, v219
	v_cvt_pk_fp8_f32 v252, v179, v254 op_sel:[0,0,1]
	s_waitcnt lgkmcnt(2)
	v_mfma_scale_f32_32x32x64_f8f6f4 v[114:129], v[90:97], v[130:137], v[114:129], v194, v193 op_sel_hi:[0,0,0]
	v_exp_f32_e32 v0, v78
	v_exp_f32_e32 v177, v79
	v_exp_f32_e32 v179, v80
	v_exp_f32_e32 v254, v81
	v_add_f32_e32 v219, v0, v219
	v_add_f32_e32 v219, v177, v219
	v_cvt_pk_fp8_f32 v253, v0, v177
	v_add_f32_e32 v219, v179, v219
	v_add_f32_e32 v219, v254, v219
	v_cvt_pk_fp8_f32 v253, v179, v254 op_sel:[0,0,1]
	ds_read_b128 v[90:93], v185 offset:43008
	ds_read_b128 v[94:97], v186 offset:43008
	ds_read_b128 v[82:85], v185 offset:45056
	ds_read_b128 v[86:89], v186 offset:45056
	ds_read_b128 v[74:77], v185 offset:47104
	ds_read_b128 v[78:81], v186 offset:47104
	ds_read_b128 v[66:69], v185 offset:49152
	ds_read_b128 v[70:73], v186 offset:49152
	s_waitcnt vmcnt(0)
	ds_write_b128 v210, v[158:161] offset:8192
	ds_write_b128 v211, v[162:165] offset:24576
	s_waitcnt lgkmcnt(10)
	v_mfma_scale_f32_32x32x64_f8f6f4 v[98:113], v[222:229], v[130:137], v[98:113], v194, v193 op_sel_hi:[0,0,0]
	s_waitcnt lgkmcnt(0)
	s_barrier
	global_load_dwordx4 v[158:161], v176, s[18:19]
	global_load_dwordx4 v[162:165], v178, s[16:17]
	v_add_u32_e32 v176, 0x2000, v176
	v_add_u32_e32 v178, 0x20000, v178
	v_mov_b32_e32 v0, v219
	s_nop 1
	v_permlane32_swap_b32_e32 v219, v0
	v_add_f32_e32 v219, v219, v0
	v_fma_f32 v209, v209, v218, v219
	v_max_f32_e32 v177, v114, v115
	v_max3_f32 v177, v177, v116, v117
	v_max3_f32 v177, v177, v118, v119
	v_max3_f32 v177, v177, v120, v121
	v_max3_f32 v177, v177, v122, v123
	v_max3_f32 v177, v177, v124, v125
	v_max3_f32 v177, v177, v126, v127
	v_max3_f32 v177, v177, v128, v129
	s_waitcnt lgkmcnt(6)
	v_mfma_scale_f32_32x32x64_f8f6f4 v[50:65], v[246:253], v[90:97], v[50:65], v194, v194 op_sel_hi:[0,0,0]
	s_waitcnt lgkmcnt(4)
	v_mfma_scale_f32_32x32x64_f8f6f4 v[34:49], v[246:253], v[82:89], v[34:49], v194, v194 op_sel_hi:[0,0,0]
	s_waitcnt lgkmcnt(2)
	v_mfma_scale_f32_32x32x64_f8f6f4 v[18:33], v[246:253], v[74:81], v[18:33], v194, v194 op_sel_hi:[0,0,0]
	s_waitcnt lgkmcnt(0)
	v_mfma_scale_f32_32x32x64_f8f6f4 v[2:17], v[246:253], v[66:73], v[2:17], v194, v194 op_sel_hi:[0,0,0]
	v_max_f32_e32 v0, v98, v99
	v_max3_f32 v0, v0, v100, v101
	v_max3_f32 v0, v0, v102, v103
	v_max3_f32 v0, v0, v104, v105
	v_max3_f32 v0, v0, v106, v107
	v_max3_f32 v0, v0, v108, v109
	v_max3_f32 v0, v0, v110, v111
	v_max3_f32 v0, v0, v112, v113
	v_max_f32_e32 v177, v177, v0
	v_mov_b32_e32 v0, v177
	v_mov_b32_e32 v221, 1.0
	s_nop 0
	v_permlane32_swap_b32_e32 v177, v0
	v_max_f32_e32 v177, v177, v0
	v_cmp_ge_f32_e32 vcc, s90, v177
	s_cmp_eq_u64 vcc, exec
	s_cbranch_scc0 .Lmla_s2_newmax
; __device__ __forceinline__ void finishSM9(f32x16& p0, f32x16& p1, float alpha, float& l_reg, v8i32& p8) {
; #pragma unroll
;   for (int r = 0; r < 16; ++r) { p0[r] = __builtin_amdgcn_exp2f(p0[r]); p1[r] = __builtin_amdgcn_exp2f(p1[r]); }
;   float ps = 0;
; #pragma unroll
;   for (int r = 0; r < 16; ++r) ps += p0[r];
; #pragma unroll
;   for (int r = 0; r < 16; ++r) ps += p1[r];
;   { auto rr = __builtin_amdgcn_permlane32_swap(__float_as_uint(ps), __float_as_uint(ps), false, false);
;     ps = __uint_as_float(rr[0]) + __uint_as_float(rr[1]); }
;   l_reg = l_reg * alpha + ps;
; #pragma unroll
;   for (int g = 0; g < 4; ++g) {
;     int w = __builtin_amdgcn_cvt_pk_fp8_f32(p0[4 * g], p0[4 * g + 1], 0, false); p8[g] = __builtin_amdgcn_cvt_pk_fp8_f32(p0[4 * g + 2], p0[4 * g + 3], w, true);
;     int u = __builtin_amdgcn_cvt_pk_fp8_f32(p1[4 * g], p1[4 * g + 1], 0, false); p8[4 + g] = __builtin_amdgcn_cvt_pk_fp8_f32(p1[4 * g + 2], p1[4 * g + 3], u, true); }
; }
; __device__ __forceinline__ void pv8(f32x16* o, const char* Vt, const v8i32 p8, int r32, int hi) {
;   const int sw = (r32 >> 2) & 3, a0 = r32 * 64 + (((hi * 2) ^ sw) << 4), a1 = r32 * 64 + (((hi * 2 + 1) ^ sw) << 4);
; #pragma unroll
;   for (int d0 = 0; d0 < 4; ++d0) {
;     const v8i32 vf = cat8(*reinterpret_cast<const v4i32*>(Vt + d0 * 2048 + a0), *reinterpret_cast<const v4i32*>(Vt + d0 * 2048 + a1));
;     o[d0] = __builtin_amdgcn_mfma_scale_f32_32x32x64_f8f6f4(p8, vf, o[d0], 0, 0, 0, 127, 0, 127); }
; }
; __device__ __forceinline__ void qkt9(f32x16& p0, f32x16& p1, const char* Kn, const char* Kr, const v8i32* qf, const float init, int r32, int hi) {
; #pragma unroll
;   for (int r = 0; r < 16; ++r) { p0[r] = init; p1[r] = init; }
; #pragma unroll
;   for (int s = 0; s < 2; ++s) { const int c0 = s * 4 + hi * 2;
;     const v8i32 a0 = cat8(*reinterpret_cast<const v4i32*>(Kn + KN8SW(r32, c0)), *reinterpret_cast<const v4i32*>(Kn + KN8SW(r32, c0 + 1)));
;     const v8i32 a1 = cat8(*reinterpret_cast<const v4i32*>(Kn + 4096 + KN8SW(r32, c0)), *reinterpret_cast<const v4i32*>(Kn + 4096 + KN8SW(r32, c0 + 1)));
;     p0 = __builtin_amdgcn_mfma_scale_f32_32x32x64_f8f6f4(a0, qf[s], p0, 0, 0, 0, 127, 0, 124);
;     p1 = __builtin_amdgcn_mfma_scale_f32_32x32x64_f8f6f4(a1, qf[s], p1, 0, 0, 0, 127, 0, 124); }
;   { const int c0 = hi * 2;
.Lmla_s2_cont:
	ds_read_b128 v[82:85], v215 offset:24576
	ds_read_b128 v[86:89], v216 offset:24576
	ds_read_b128 v[222:225], v215 offset:28672
	ds_read_b128 v[226:229], v216 offset:28672
	v_exp_f32_e32 v0, v114
	v_exp_f32_e32 v177, v115
	v_exp_f32_e32 v179, v116
	v_exp_f32_e32 v254, v117
	v_add_f32_e32 v219, v0, v177
	v_cvt_pk_fp8_f32 v246, v0, v177
	v_add_f32_e32 v219, v179, v219
	v_add_f32_e32 v219, v254, v219
	v_cvt_pk_fp8_f32 v246, v179, v254 op_sel:[0,0,1]
	s_waitcnt lgkmcnt(2)
	v_mfma_scale_f32_32x32x64_f8f6f4 v[82:97], v[82:89], v[146:153], v[230:245], v194, v193 op_sel_hi:[0,0,0]
	v_exp_f32_e32 v0, v118
	v_exp_f32_e32 v177, v119
	v_exp_f32_e32 v179, v120
	v_exp_f32_e32 v254, v121
	v_add_f32_e32 v219, v0, v219
	v_add_f32_e32 v219, v177, v219
	v_cvt_pk_fp8_f32 v247, v0, v177
	v_add_f32_e32 v219, v179, v219
	v_add_f32_e32 v219, v254, v219
	v_cvt_pk_fp8_f32 v247, v179, v254 op_sel:[0,0,1]
	ds_read_b128 v[114:117], v213 offset:24576
	ds_read_b128 v[118:121], v214 offset:24576
	s_waitcnt lgkmcnt(2)
	v_mfma_scale_f32_32x32x64_f8f6f4 v[66:81], v[222:229], v[146:153], v[230:245], v194, v193 op_sel_hi:[0,0,0]
	ds_read_b128 v[222:225], v213 offset:28672
	ds_read_b128 v[226:229], v214 offset:28672
	v_exp_f32_e32 v0, v122
	v_exp_f32_e32 v177, v123
	v_exp_f32_e32 v179, v124
	v_exp_f32_e32 v254, v125
	v_add_f32_e32 v219, v0, v219
	v_add_f32_e32 v219, v177, v219
	v_cvt_pk_fp8_f32 v248, v0, v177
	v_add_f32_e32 v219, v179, v219
	v_add_f32_e32 v219, v254, v219
	v_cvt_pk_fp8_f32 v248, v179, v254 op_sel:[0,0,1]
	v_exp_f32_e32 v0, v126
	v_exp_f32_e32 v177, v127
	v_exp_f32_e32 v179, v128
	v_exp_f32_e32 v254, v129
	v_add_f32_e32 v219, v0, v219
	v_add_f32_e32 v219, v177, v219
	v_cvt_pk_fp8_f32 v249, v0, v177
	v_add_f32_e32 v219, v179, v219
	v_add_f32_e32 v219, v254, v219
	v_cvt_pk_fp8_f32 v249, v179, v254 op_sel:[0,0,1]
	ds_read_b128 v[122:125], v185 offset:36864
	ds_read_b128 v[126:129], v186 offset:36864
	s_waitcnt lgkmcnt(4)
	v_mfma_scale_f32_32x32x64_f8f6f4 v[82:97], v[114:121], v[138:145], v[82:97], v194, v193 op_sel_hi:[0,0,0]
	v_exp_f32_e32 v0, v98
	v_exp_f32_e32 v177, v99
	v_exp_f32_e32 v179, v100
	v_exp_f32_e32 v254, v101
	v_add_f32_e32 v219, v0, v219
	v_add_f32_e32 v219, v177, v219
	v_cvt_pk_fp8_f32 v250, v0, v177
	v_add_f32_e32 v219, v179, v219
	v_add_f32_e32 v219, v254, v219
	v_cvt_pk_fp8_f32 v250, v179, v254 op_sel:[0,0,1]
	s_waitcnt lgkmcnt(2)
	v_mfma_scale_f32_32x32x64_f8f6f4 v[66:81], v[222:229], v[138:145], v[66:81], v194, v193 op_sel_hi:[0,0,0]
	ds_read_b128 v[222:225], v185 offset:38912
	ds_read_b128 v[226:229], v186 offset:38912
	v_exp_f32_e32 v0, v102
	v_exp_f32_e32 v177, v103
	v_exp_f32_e32 v179, v104
	v_exp_f32_e32 v254, v105
	v_add_f32_e32 v219, v0, v219
	v_add_f32_e32 v219, v177, v219
	v_cvt_pk_fp8_f32 v251, v0, v177
	v_add_f32_e32 v219, v179, v219
	v_add_f32_e32 v219, v254, v219
	v_cvt_pk_fp8_f32 v251, v179, v254 op_sel:[0,0,1]
	v_exp_f32_e32 v0, v106
	v_exp_f32_e32 v177, v107
	v_exp_f32_e32 v179, v108
	v_exp_f32_e32 v254, v109
	v_add_f32_e32 v219, v0, v219
	v_add_f32_e32 v219, v177, v219
	v_cvt_pk_fp8_f32 v252, v0, v177
	v_add_f32_e32 v219, v179, v219
	v_add_f32_e32 v219, v254, v219
	v_cvt_pk_fp8_f32 v252, v179, v254 op_sel:[0,0,1]
	s_waitcnt lgkmcnt(2)
	v_mfma_scale_f32_32x32x64_f8f6f4 v[82:97], v[122:129], v[130:137], v[82:97], v194, v193 op_sel_hi:[0,0,0]
	v_exp_f32_e32 v0, v110
	v_exp_f32_e32 v177, v111
	v_exp_f32_e32 v179, v112
	v_exp_f32_e32 v254, v113
	v_add_f32_e32 v219, v0, v219
	v_add_f32_e32 v219, v177, v219
	v_cvt_pk_fp8_f32 v253, v0, v177
	v_add_f32_e32 v219, v179, v219
	v_add_f32_e32 v219, v254, v219
	v_cvt_pk_fp8_f32 v253, v179, v254 op_sel:[0,0,1]
	ds_read_b128 v[122:125], v185 offset:0
	ds_read_b128 v[126:129], v186 offset:0
	ds_read_b128 v[114:117], v185 offset:2048
	ds_read_b128 v[118:121], v186 offset:2048
	ds_read_b128 v[106:109], v185 offset:4096
	ds_read_b128 v[110:113], v186 offset:4096
	ds_read_b128 v[98:101], v185 offset:6144
	ds_read_b128 v[102:105], v186 offset:6144
	s_waitcnt vmcnt(0)
	ds_write_b128 v210, v[158:161] offset:43008
	ds_write_b128 v211, v[162:165] offset:51200
	s_waitcnt lgkmcnt(10)
	v_mfma_scale_f32_32x32x64_f8f6f4 v[66:81], v[222:229], v[130:137], v[66:81], v194, v193 op_sel_hi:[0,0,0]
	s_waitcnt lgkmcnt(0)
	s_barrier
	global_load_dwordx4 v[158:161], v176, s[18:19]
	global_load_dwordx4 v[162:165], v178, s[16:17]
	v_add_u32_e32 v176, 0x2000, v176
	v_add_u32_e32 v178, 0x20000, v178
	v_mov_b32_e32 v0, v219
	s_nop 1
	v_permlane32_swap_b32_e32 v219, v0
	v_add_f32_e32 v219, v219, v0
	v_fma_f32 v209, v209, v221, v219
	v_max_f32_e32 v177, v82, v83
	v_max3_f32 v177, v177, v84, v85
	v_max3_f32 v177, v177, v86, v87
	v_max3_f32 v177, v177, v88, v89
	v_max3_f32 v177, v177, v90, v91
	v_max3_f32 v177, v177, v92, v93
	v_max3_f32 v177, v177, v94, v95
	v_max3_f32 v177, v177, v96, v97
	s_waitcnt lgkmcnt(6)
	v_mfma_scale_f32_32x32x64_f8f6f4 v[50:65], v[246:253], v[122:129], v[50:65], v194, v194 op_sel_hi:[0,0,0]
	s_waitcnt lgkmcnt(4)
	v_mfma_scale_f32_32x32x64_f8f6f4 v[34:49], v[246:253], v[114:121], v[34:49], v194, v194 op_sel_hi:[0,0,0]
	s_waitcnt lgkmcnt(2)
	v_mfma_scale_f32_32x32x64_f8f6f4 v[18:33], v[246:253], v[106:113], v[18:33], v194, v194 op_sel_hi:[0,0,0]
	s_waitcnt lgkmcnt(0)
	v_mfma_scale_f32_32x32x64_f8f6f4 v[2:17], v[246:253], v[98:105], v[2:17], v194, v194 op_sel_hi:[0,0,0]
	v_max_f32_e32 v0, v66, v67
	v_max3_f32 v0, v0, v68, v69
	v_max3_f32 v0, v0, v70, v71
	v_max3_f32 v0, v0, v72, v73
	v_max3_f32 v0, v0, v74, v75
	v_max3_f32 v0, v0, v76, v77
	v_max3_f32 v0, v0, v78, v79
	v_max3_f32 v0, v0, v80, v81
	v_max_f32_e32 v177, v177, v0
	v_mov_b32_e32 v0, v177
	v_mov_b32_e32 v218, 1.0
	s_nop 0
	v_permlane32_swap_b32_e32 v177, v0
	v_max_f32_e32 v177, v177, v0
	v_cmp_ge_f32_e32 vcc, s90, v177
	s_cmp_eq_u64 vcc, exec
	s_cbranch_scc0 .Lmla_s3_newmax
; __device__ __forceinline__ void finishSM9(f32x16& p0, f32x16& p1, float alpha, float& l_reg, v8i32& p8) {
; #pragma unroll
;   for (int r = 0; r < 16; ++r) { p0[r] = __builtin_amdgcn_exp2f(p0[r]); p1[r] = __builtin_amdgcn_exp2f(p1[r]); }
;   float ps = 0;
; #pragma unroll
;   for (int r = 0; r < 16; ++r) ps += p0[r];
; #pragma unroll
;   for (int r = 0; r < 16; ++r) ps += p1[r];
;   { auto rr = __builtin_amdgcn_permlane32_swap(__float_as_uint(ps), __float_as_uint(ps), false, false);
;     ps = __uint_as_float(rr[0]) + __uint_as_float(rr[1]); }
;   l_reg = l_reg * alpha + ps;
; #pragma unroll
;   for (int g = 0; g < 4; ++g) {
;     int w = __builtin_amdgcn_cvt_pk_fp8_f32(p0[4 * g], p0[4 * g + 1], 0, false); p8[g] = __builtin_amdgcn_cvt_pk_fp8_f32(p0[4 * g + 2], p0[4 * g + 3], w, true);
;     int u = __builtin_amdgcn_cvt_pk_fp8_f32(p1[4 * g], p1[4 * g + 1], 0, false); p8[4 + g] = __builtin_amdgcn_cvt_pk_fp8_f32(p1[4 * g + 2], p1[4 * g + 3], u, true); }
; }
; __device__ __forceinline__ void pv8(f32x16* o, const char* Vt, const v8i32 p8, int r32, int hi) {
;   const int sw = (r32 >> 2) & 3, a0 = r32 * 64 + (((hi * 2) ^ sw) << 4), a1 = r32 * 64 + (((hi * 2 + 1) ^ sw) << 4);
; #pragma unroll
;   for (int d0 = 0; d0 < 4; ++d0) {
;     const v8i32 vf = cat8(*reinterpret_cast<const v4i32*>(Vt + d0 * 2048 + a0), *reinterpret_cast<const v4i32*>(Vt + d0 * 2048 + a1));
;     o[d0] = __builtin_amdgcn_mfma_scale_f32_32x32x64_f8f6f4(p8, vf, o[d0], 0, 0, 0, 127, 0, 127); }
; }
; __device__ __forceinline__ void qkt9(f32x16& p0, f32x16& p1, const char* Kn, const char* Kr, const v8i32* qf, const float init, int r32, int hi) {
; #pragma unroll
;   for (int r = 0; r < 16; ++r) { p0[r] = init; p1[r] = init; }
; #pragma unroll
;   for (int s = 0; s < 2; ++s) { const int c0 = s * 4 + hi * 2;
;     const v8i32 a0 = cat8(*reinterpret_cast<const v4i32*>(Kn + KN8SW(r32, c0)), *reinterpret_cast<const v4i32*>(Kn + KN8SW(r32, c0 + 1)));
;     const v8i32 a1 = cat8(*reinterpret_cast<const v4i32*>(Kn + 4096 + KN8SW(r32, c0)), *reinterpret_cast<const v4i32*>(Kn + 4096 + KN8SW(r32, c0 + 1)));
;     p0 = __builtin_amdgcn_mfma_scale_f32_32x32x64_f8f6f4(a0, qf[s], p0, 0, 0, 0, 127, 0, 124);
;     p1 = __builtin_amdgcn_mfma_scale_f32_32x32x64_f8f6f4(a1, qf[s], p1, 0, 0, 0, 127, 0, 124); }
;   { const int c0 = hi * 2;
.Lmla_s3_cont:
	ds_read_b128 v[114:117], v215 offset:51200
	ds_read_b128 v[118:121], v216 offset:51200
	ds_read_b128 v[222:225], v215 offset:55296
	ds_read_b128 v[226:229], v216 offset:55296
	v_exp_f32_e32 v0, v82
	v_exp_f32_e32 v177, v83
	v_exp_f32_e32 v179, v84
	v_exp_f32_e32 v254, v85
	v_add_f32_e32 v219, v0, v177
	v_cvt_pk_fp8_f32 v246, v0, v177
	v_add_f32_e32 v219, v179, v219
	v_add_f32_e32 v219, v254, v219
	v_cvt_pk_fp8_f32 v246, v179, v254 op_sel:[0,0,1]
	s_waitcnt lgkmcnt(2)
	v_mfma_scale_f32_32x32x64_f8f6f4 v[114:129], v[114:121], v[146:153], v[230:245], v194, v193 op_sel_hi:[0,0,0]
	v_exp_f32_e32 v0, v86
	v_exp_f32_e32 v177, v87
	v_exp_f32_e32 v179, v88
	v_exp_f32_e32 v254, v89
	v_add_f32_e32 v219, v0, v219
	v_add_f32_e32 v219, v177, v219
	v_cvt_pk_fp8_f32 v247, v0, v177
	v_add_f32_e32 v219, v179, v219
	v_add_f32_e32 v219, v254, v219
	v_cvt_pk_fp8_f32 v247, v179, v254 op_sel:[0,0,1]
	ds_read_b128 v[82:85], v213 offset:51200
	ds_read_b128 v[86:89], v214 offset:51200
	s_waitcnt lgkmcnt(2)
	v_mfma_scale_f32_32x32x64_f8f6f4 v[98:113], v[222:229], v[146:153], v[230:245], v194, v193 op_sel_hi:[0,0,0]
	ds_read_b128 v[222:225], v213 offset:55296
	ds_read_b128 v[226:229], v214 offset:55296
	v_exp_f32_e32 v0, v90
	v_exp_f32_e32 v177, v91
	v_exp_f32_e32 v179, v92
	v_exp_f32_e32 v254, v93
	v_add_f32_e32 v219, v0, v219
	v_add_f32_e32 v219, v177, v219
	v_cvt_pk_fp8_f32 v248, v0, v177
	v_add_f32_e32 v219, v179, v219
	v_add_f32_e32 v219, v254, v219
	v_cvt_pk_fp8_f32 v248, v179, v254 op_sel:[0,0,1]
	v_exp_f32_e32 v0, v94
	v_exp_f32_e32 v177, v95
	v_exp_f32_e32 v179, v96
	v_exp_f32_e32 v254, v97
	v_add_f32_e32 v219, v0, v219
	v_add_f32_e32 v219, v177, v219
	v_cvt_pk_fp8_f32 v249, v0, v177
	v_add_f32_e32 v219, v179, v219
	v_add_f32_e32 v219, v254, v219
	v_cvt_pk_fp8_f32 v249, v179, v254 op_sel:[0,0,1]
	ds_read_b128 v[90:93], v185 offset:59392
	ds_read_b128 v[94:97], v186 offset:59392
	s_waitcnt lgkmcnt(4)
	v_mfma_scale_f32_32x32x64_f8f6f4 v[114:129], v[82:89], v[138:145], v[114:129], v194, v193 op_sel_hi:[0,0,0]
	v_exp_f32_e32 v0, v66
	v_exp_f32_e32 v177, v67
	v_exp_f32_e32 v179, v68
	v_exp_f32_e32 v254, v69
	v_add_f32_e32 v219, v0, v219
	v_add_f32_e32 v219, v177, v219
	v_cvt_pk_fp8_f32 v250, v0, v177
	v_add_f32_e32 v219, v179, v219
	v_add_f32_e32 v219, v254, v219
	v_cvt_pk_fp8_f32 v250, v179, v254 op_sel:[0,0,1]
	s_waitcnt lgkmcnt(2)
	v_mfma_scale_f32_32x32x64_f8f6f4 v[98:113], v[222:229], v[138:145], v[98:113], v194, v193 op_sel_hi:[0,0,0]
	ds_read_b128 v[222:225], v185 offset:61440
	ds_read_b128 v[226:229], v186 offset:61440
	v_exp_f32_e32 v0, v70
	v_exp_f32_e32 v177, v71
	v_exp_f32_e32 v179, v72
	v_exp_f32_e32 v254, v73
	v_add_f32_e32 v219, v0, v219
	v_add_f32_e32 v219, v177, v219
	v_cvt_pk_fp8_f32 v251, v0, v177
	v_add_f32_e32 v219, v179, v219
	v_add_f32_e32 v219, v254, v219
	v_cvt_pk_fp8_f32 v251, v179, v254 op_sel:[0,0,1]
	v_exp_f32_e32 v0, v74
	v_exp_f32_e32 v177, v75
	v_exp_f32_e32 v179, v76
	v_exp_f32_e32 v254, v77
	v_add_f32_e32 v219, v0, v219
	v_add_f32_e32 v219, v177, v219
	v_cvt_pk_fp8_f32 v252, v0, v177
	v_add_f32_e32 v219, v179, v219
	v_add_f32_e32 v219, v254, v219
	v_cvt_pk_fp8_f32 v252, v179, v254 op_sel:[0,0,1]
	s_waitcnt lgkmcnt(2)
	v_mfma_scale_f32_32x32x64_f8f6f4 v[114:129], v[90:97], v[130:137], v[114:129], v194, v193 op_sel_hi:[0,0,0]
	v_exp_f32_e32 v0, v78
	v_exp_f32_e32 v177, v79
	v_exp_f32_e32 v179, v80
	v_exp_f32_e32 v254, v81
	v_add_f32_e32 v219, v0, v219
	v_add_f32_e32 v219, v177, v219
	v_cvt_pk_fp8_f32 v253, v0, v177
	v_add_f32_e32 v219, v179, v219
	v_add_f32_e32 v219, v254, v219
	v_cvt_pk_fp8_f32 v253, v179, v254 op_sel:[0,0,1]
	ds_read_b128 v[90:93], v185 offset:8192
	ds_read_b128 v[94:97], v186 offset:8192
	ds_read_b128 v[82:85], v185 offset:10240
	ds_read_b128 v[86:89], v186 offset:10240
	ds_read_b128 v[74:77], v185 offset:12288
	ds_read_b128 v[78:81], v186 offset:12288
	ds_read_b128 v[66:69], v185 offset:14336
	ds_read_b128 v[70:73], v186 offset:14336
	s_waitcnt vmcnt(0)
	ds_write_b128 v210, v[158:161]
	ds_write_b128 v211, v[162:165] offset:16384
	s_waitcnt lgkmcnt(10)
	v_mfma_scale_f32_32x32x64_f8f6f4 v[98:113], v[222:229], v[130:137], v[98:113], v194, v193 op_sel_hi:[0,0,0]
	s_waitcnt lgkmcnt(0)
	s_barrier
	global_load_dwordx4 v[158:161], v176, s[18:19]
	global_load_dwordx4 v[162:165], v178, s[16:17]
	v_add_u32_e32 v176, 0x2000, v176
	v_add_u32_e32 v178, 0x20000, v178
	v_mov_b32_e32 v0, v219
	s_nop 1
	v_permlane32_swap_b32_e32 v219, v0
	v_add_f32_e32 v219, v219, v0
	v_fma_f32 v209, v209, v218, v219
	v_max_f32_e32 v177, v114, v115
	v_max3_f32 v177, v177, v116, v117
	v_max3_f32 v177, v177, v118, v119
	v_max3_f32 v177, v177, v120, v121
	v_max3_f32 v177, v177, v122, v123
	v_max3_f32 v177, v177, v124, v125
	v_max3_f32 v177, v177, v126, v127
	v_max3_f32 v177, v177, v128, v129
	s_waitcnt lgkmcnt(6)
	v_mfma_scale_f32_32x32x64_f8f6f4 v[50:65], v[246:253], v[90:97], v[50:65], v194, v194 op_sel_hi:[0,0,0]
	s_waitcnt lgkmcnt(4)
	v_mfma_scale_f32_32x32x64_f8f6f4 v[34:49], v[246:253], v[82:89], v[34:49], v194, v194 op_sel_hi:[0,0,0]
	s_waitcnt lgkmcnt(2)
	v_mfma_scale_f32_32x32x64_f8f6f4 v[18:33], v[246:253], v[74:81], v[18:33], v194, v194 op_sel_hi:[0,0,0]
	s_waitcnt lgkmcnt(0)
	v_mfma_scale_f32_32x32x64_f8f6f4 v[2:17], v[246:253], v[66:73], v[2:17], v194, v194 op_sel_hi:[0,0,0]
	v_max_f32_e32 v0, v98, v99
	v_max3_f32 v0, v0, v100, v101
	v_max3_f32 v0, v0, v102, v103
	v_max3_f32 v0, v0, v104, v105
	v_max3_f32 v0, v0, v106, v107
	v_max3_f32 v0, v0, v108, v109
	v_max3_f32 v0, v0, v110, v111
	v_max3_f32 v0, v0, v112, v113
	v_max_f32_e32 v177, v177, v0
	v_mov_b32_e32 v0, v177
	v_mov_b32_e32 v221, 1.0
	s_nop 0
	v_permlane32_swap_b32_e32 v177, v0
	v_max_f32_e32 v177, v177, v0
	v_cmp_ge_f32_e32 vcc, s90, v177
	s_cmp_eq_u64 vcc, exec
	s_cbranch_scc0 .Lmla_s4_newmax
; __device__ __forceinline__ void finishSM9(f32x16& p0, f32x16& p1, float alpha, float& l_reg, v8i32& p8) {
; #pragma unroll
;   for (int r = 0; r < 16; ++r) { p0[r] = __builtin_amdgcn_exp2f(p0[r]); p1[r] = __builtin_amdgcn_exp2f(p1[r]); }
;   float ps = 0;
; #pragma unroll
;   for (int r = 0; r < 16; ++r) ps += p0[r];
; #pragma unroll
;   for (int r = 0; r < 16; ++r) ps += p1[r];
;   { auto rr = __builtin_amdgcn_permlane32_swap(__float_as_uint(ps), __float_as_uint(ps), false, false);
;     ps = __uint_as_float(rr[0]) + __uint_as_float(rr[1]); }
;   l_reg = l_reg * alpha + ps;
; #pragma unroll
;   for (int g = 0; g < 4; ++g) {
;     int w = __builtin_amdgcn_cvt_pk_fp8_f32(p0[4 * g], p0[4 * g + 1], 0, false); p8[g] = __builtin_amdgcn_cvt_pk_fp8_f32(p0[4 * g + 2], p0[4 * g + 3], w, true);
;     int u = __builtin_amdgcn_cvt_pk_fp8_f32(p1[4 * g], p1[4 * g + 1], 0, false); p8[4 + g] = __builtin_amdgcn_cvt_pk_fp8_f32(p1[4 * g + 2], p1[4 * g + 3], u, true); }
; }
; __device__ __forceinline__ void pv8(f32x16* o, const char* Vt, const v8i32 p8, int r32, int hi) {
;   const int sw = (r32 >> 2) & 3, a0 = r32 * 64 + (((hi * 2) ^ sw) << 4), a1 = r32 * 64 + (((hi * 2 + 1) ^ sw) << 4);
; #pragma unroll
;   for (int d0 = 0; d0 < 4; ++d0) {
;     const v8i32 vf = cat8(*reinterpret_cast<const v4i32*>(Vt + d0 * 2048 + a0), *reinterpret_cast<const v4i32*>(Vt + d0 * 2048 + a1));
;     o[d0] = __builtin_amdgcn_mfma_scale_f32_32x32x64_f8f6f4(p8, vf, o[d0], 0, 0, 0, 127, 0, 127); }
; }
; __device__ __forceinline__ void qkt9(f32x16& p0, f32x16& p1, const char* Kn, const char* Kr, const v8i32* qf, const float init, int r32, int hi) {
; #pragma unroll
;   for (int r = 0; r < 16; ++r) { p0[r] = init; p1[r] = init; }
; #pragma unroll
;   for (int s = 0; s < 2; ++s) { const int c0 = s * 4 + hi * 2;
;     const v8i32 a0 = cat8(*reinterpret_cast<const v4i32*>(Kn + KN8SW(r32, c0)), *reinterpret_cast<const v4i32*>(Kn + KN8SW(r32, c0 + 1)));
;     const v8i32 a1 = cat8(*reinterpret_cast<const v4i32*>(Kn + 4096 + KN8SW(r32, c0)), *reinterpret_cast<const v4i32*>(Kn + 4096 + KN8SW(r32, c0 + 1)));
;     p0 = __builtin_amdgcn_mfma_scale_f32_32x32x64_f8f6f4(a0, qf[s], p0, 0, 0, 0, 127, 0, 124);
;     p1 = __builtin_amdgcn_mfma_scale_f32_32x32x64_f8f6f4(a1, qf[s], p1, 0, 0, 0, 127, 0, 124); }
;   { const int c0 = hi * 2;
.Lmla_s4_cont:
	ds_read_b128 v[82:85], v215 offset:16384
	ds_read_b128 v[86:89], v216 offset:16384
	ds_read_b128 v[222:225], v215 offset:20480
	ds_read_b128 v[226:229], v216 offset:20480
	v_exp_f32_e32 v0, v114
	v_exp_f32_e32 v177, v115
	v_exp_f32_e32 v179, v116
	v_exp_f32_e32 v254, v117
	v_add_f32_e32 v219, v0, v177
	v_cvt_pk_fp8_f32 v246, v0, v177
	v_add_f32_e32 v219, v179, v219
	v_add_f32_e32 v219, v254, v219
	v_cvt_pk_fp8_f32 v246, v179, v254 op_sel:[0,0,1]
	s_waitcnt lgkmcnt(2)
	v_mfma_scale_f32_32x32x64_f8f6f4 v[82:97], v[82:89], v[146:153], v[230:245], v194, v193 op_sel_hi:[0,0,0]
	v_exp_f32_e32 v0, v118
	v_exp_f32_e32 v177, v119
	v_exp_f32_e32 v179, v120
	v_exp_f32_e32 v254, v121
	v_add_f32_e32 v219, v0, v219
	v_add_f32_e32 v219, v177, v219
	v_cvt_pk_fp8_f32 v247, v0, v177
	v_add_f32_e32 v219, v179, v219
	v_add_f32_e32 v219, v254, v219
	v_cvt_pk_fp8_f32 v247, v179, v254 op_sel:[0,0,1]
	ds_read_b128 v[114:117], v213 offset:16384
	ds_read_b128 v[118:121], v214 offset:16384
	s_waitcnt lgkmcnt(2)
	v_mfma_scale_f32_32x32x64_f8f6f4 v[66:81], v[222:229], v[146:153], v[230:245], v194, v193 op_sel_hi:[0,0,0]
	ds_read_b128 v[222:225], v213 offset:20480
	ds_read_b128 v[226:229], v214 offset:20480
	v_exp_f32_e32 v0, v122
	v_exp_f32_e32 v177, v123
	v_exp_f32_e32 v179, v124
	v_exp_f32_e32 v254, v125
	v_add_f32_e32 v219, v0, v219
	v_add_f32_e32 v219, v177, v219
	v_cvt_pk_fp8_f32 v248, v0, v177
	v_add_f32_e32 v219, v179, v219
	v_add_f32_e32 v219, v254, v219
	v_cvt_pk_fp8_f32 v248, v179, v254 op_sel:[0,0,1]
	v_exp_f32_e32 v0, v126
	v_exp_f32_e32 v177, v127
	v_exp_f32_e32 v179, v128
	v_exp_f32_e32 v254, v129
	v_add_f32_e32 v219, v0, v219
	v_add_f32_e32 v219, v177, v219
	v_cvt_pk_fp8_f32 v249, v0, v177
	v_add_f32_e32 v219, v179, v219
	v_add_f32_e32 v219, v254, v219
	v_cvt_pk_fp8_f32 v249, v179, v254 op_sel:[0,0,1]
	ds_read_b128 v[122:125], v185 offset:32768
	ds_read_b128 v[126:129], v186 offset:32768
	s_waitcnt lgkmcnt(4)
	v_mfma_scale_f32_32x32x64_f8f6f4 v[82:97], v[114:121], v[138:145], v[82:97], v194, v193 op_sel_hi:[0,0,0]
	v_exp_f32_e32 v0, v98
	v_exp_f32_e32 v177, v99
	v_exp_f32_e32 v179, v100
	v_exp_f32_e32 v254, v101
	v_add_f32_e32 v219, v0, v219
	v_add_f32_e32 v219, v177, v219
	v_cvt_pk_fp8_f32 v250, v0, v177
	v_add_f32_e32 v219, v179, v219
	v_add_f32_e32 v219, v254, v219
	v_cvt_pk_fp8_f32 v250, v179, v254 op_sel:[0,0,1]
	s_waitcnt lgkmcnt(2)
	v_mfma_scale_f32_32x32x64_f8f6f4 v[66:81], v[222:229], v[138:145], v[66:81], v194, v193 op_sel_hi:[0,0,0]
	ds_read_b128 v[222:225], v185 offset:34816
	ds_read_b128 v[226:229], v186 offset:34816
	v_exp_f32_e32 v0, v102
	v_exp_f32_e32 v177, v103
	v_exp_f32_e32 v179, v104
	v_exp_f32_e32 v254, v105
	v_add_f32_e32 v219, v0, v219
	v_add_f32_e32 v219, v177, v219
	v_cvt_pk_fp8_f32 v251, v0, v177
	v_add_f32_e32 v219, v179, v219
	v_add_f32_e32 v219, v254, v219
	v_cvt_pk_fp8_f32 v251, v179, v254 op_sel:[0,0,1]
	v_exp_f32_e32 v0, v106
	v_exp_f32_e32 v177, v107
	v_exp_f32_e32 v179, v108
	v_exp_f32_e32 v254, v109
	v_add_f32_e32 v219, v0, v219
	v_add_f32_e32 v219, v177, v219
	v_cvt_pk_fp8_f32 v252, v0, v177
	v_add_f32_e32 v219, v179, v219
	v_add_f32_e32 v219, v254, v219
	v_cvt_pk_fp8_f32 v252, v179, v254 op_sel:[0,0,1]
	s_waitcnt lgkmcnt(2)
	v_mfma_scale_f32_32x32x64_f8f6f4 v[82:97], v[122:129], v[130:137], v[82:97], v194, v193 op_sel_hi:[0,0,0]
	v_exp_f32_e32 v0, v110
	v_exp_f32_e32 v177, v111
	v_exp_f32_e32 v179, v112
	v_exp_f32_e32 v254, v113
	v_add_f32_e32 v219, v0, v219
	v_add_f32_e32 v219, v177, v219
	v_cvt_pk_fp8_f32 v253, v0, v177
	v_add_f32_e32 v219, v179, v219
	v_add_f32_e32 v219, v254, v219
	v_cvt_pk_fp8_f32 v253, v179, v254 op_sel:[0,0,1]
	ds_read_b128 v[122:125], v185 offset:43008
	ds_read_b128 v[126:129], v186 offset:43008
	ds_read_b128 v[114:117], v185 offset:45056
	ds_read_b128 v[118:121], v186 offset:45056
	ds_read_b128 v[106:109], v185 offset:47104
	ds_read_b128 v[110:113], v186 offset:47104
	ds_read_b128 v[98:101], v185 offset:49152
	ds_read_b128 v[102:105], v186 offset:49152
	s_waitcnt vmcnt(0)
	ds_write_b128 v210, v[158:161] offset:8192
	ds_write_b128 v211, v[162:165] offset:24576
	s_waitcnt lgkmcnt(10)
	v_mfma_scale_f32_32x32x64_f8f6f4 v[66:81], v[222:229], v[130:137], v[66:81], v194, v193 op_sel_hi:[0,0,0]
	s_waitcnt lgkmcnt(0)
	s_barrier
	global_load_dwordx4 v[158:161], v176, s[18:19]
	global_load_dwordx4 v[162:165], v178, s[16:17]
	v_add_u32_e32 v176, 0x2000, v176
	v_add_u32_e32 v178, 0x20000, v178
	v_mov_b32_e32 v0, v219
	s_nop 1
	v_permlane32_swap_b32_e32 v219, v0
	v_add_f32_e32 v219, v219, v0
	v_fma_f32 v209, v209, v221, v219
	v_max_f32_e32 v177, v82, v83
	v_max3_f32 v177, v177, v84, v85
	v_max3_f32 v177, v177, v86, v87
	v_max3_f32 v177, v177, v88, v89
	v_max3_f32 v177, v177, v90, v91
	v_max3_f32 v177, v177, v92, v93
	v_max3_f32 v177, v177, v94, v95
	v_max3_f32 v177, v177, v96, v97
	s_waitcnt lgkmcnt(6)
	v_mfma_scale_f32_32x32x64_f8f6f4 v[50:65], v[246:253], v[122:129], v[50:65], v194, v194 op_sel_hi:[0,0,0]
	s_waitcnt lgkmcnt(4)
	v_mfma_scale_f32_32x32x64_f8f6f4 v[34:49], v[246:253], v[114:121], v[34:49], v194, v194 op_sel_hi:[0,0,0]
	s_waitcnt lgkmcnt(2)
	v_mfma_scale_f32_32x32x64_f8f6f4 v[18:33], v[246:253], v[106:113], v[18:33], v194, v194 op_sel_hi:[0,0,0]
	s_waitcnt lgkmcnt(0)
	v_mfma_scale_f32_32x32x64_f8f6f4 v[2:17], v[246:253], v[98:105], v[2:17], v194, v194 op_sel_hi:[0,0,0]
	v_max_f32_e32 v0, v66, v67
	v_max3_f32 v0, v0, v68, v69
	v_max3_f32 v0, v0, v70, v71
	v_max3_f32 v0, v0, v72, v73
	v_max3_f32 v0, v0, v74, v75
	v_max3_f32 v0, v0, v76, v77
	v_max3_f32 v0, v0, v78, v79
	v_max3_f32 v0, v0, v80, v81
	v_max_f32_e32 v177, v177, v0
	v_mov_b32_e32 v0, v177
	v_mov_b32_e32 v218, 1.0
	s_nop 0
	v_permlane32_swap_b32_e32 v177, v0
	v_max_f32_e32 v177, v177, v0
	v_cmp_ge_f32_e32 vcc, s90, v177
	s_cmp_eq_u64 vcc, exec
	s_cbranch_scc0 .Lmla_s5_newmax
; __device__ __forceinline__ void finishSM9(f32x16& p0, f32x16& p1, float alpha, float& l_reg, v8i32& p8) {
; #pragma unroll
;   for (int r = 0; r < 16; ++r) { p0[r] = __builtin_amdgcn_exp2f(p0[r]); p1[r] = __builtin_amdgcn_exp2f(p1[r]); }
;   float ps = 0;
; #pragma unroll
;   for (int r = 0; r < 16; ++r) ps += p0[r];
; #pragma unroll
;   for (int r = 0; r < 16; ++r) ps += p1[r];
;   { auto rr = __builtin_amdgcn_permlane32_swap(__float_as_uint(ps), __float_as_uint(ps), false, false);
;     ps = __uint_as_float(rr[0]) + __uint_as_float(rr[1]); }
;   l_reg = l_reg * alpha + ps;
; #pragma unroll
;   for (int g = 0; g < 4; ++g) {
;     int w = __builtin_amdgcn_cvt_pk_fp8_f32(p0[4 * g], p0[4 * g + 1], 0, false); p8[g] = __builtin_amdgcn_cvt_pk_fp8_f32(p0[4 * g + 2], p0[4 * g + 3], w, true);
;     int u = __builtin_amdgcn_cvt_pk_fp8_f32(p1[4 * g], p1[4 * g + 1], 0, false); p8[4 + g] = __builtin_amdgcn_cvt_pk_fp8_f32(p1[4 * g + 2], p1[4 * g + 3], u, true); }
; }
; __device__ __forceinline__ void pv8(f32x16* o, const char* Vt, const v8i32 p8, int r32, int hi) {
;   const int sw = (r32 >> 2) & 3, a0 = r32 * 64 + (((hi * 2) ^ sw) << 4), a1 = r32 * 64 + (((hi * 2 + 1) ^ sw) << 4);
; #pragma unroll
;   for (int d0 = 0; d0 < 4; ++d0) {
;     const v8i32 vf = cat8(*reinterpret_cast<const v4i32*>(Vt + d0 * 2048 + a0), *reinterpret_cast<const v4i32*>(Vt + d0 * 2048 + a1));
;     o[d0] = __builtin_amdgcn_mfma_scale_f32_32x32x64_f8f6f4(p8, vf, o[d0], 0, 0, 0, 127, 0, 127); }
; }
; __device__ __forceinline__ void qkt9(f32x16& p0, f32x16& p1, const char* Kn, const char* Kr, const v8i32* qf, const float init, int r32, int hi) {
; #pragma unroll
;   for (int r = 0; r < 16; ++r) { p0[r] = init; p1[r] = init; }
; #pragma unroll
;   for (int s = 0; s < 2; ++s) { const int c0 = s * 4 + hi * 2;
;     const v8i32 a0 = cat8(*reinterpret_cast<const v4i32*>(Kn + KN8SW(r32, c0)), *reinterpret_cast<const v4i32*>(Kn + KN8SW(r32, c0 + 1)));
;     const v8i32 a1 = cat8(*reinterpret_cast<const v4i32*>(Kn + 4096 + KN8SW(r32, c0)), *reinterpret_cast<const v4i32*>(Kn + 4096 + KN8SW(r32, c0 + 1)));
;     p0 = __builtin_amdgcn_mfma_scale_f32_32x32x64_f8f6f4(a0, qf[s], p0, 0, 0, 0, 127, 0, 124);
;     p1 = __builtin_amdgcn_mfma_scale_f32_32x32x64_f8f6f4(a1, qf[s], p1, 0, 0, 0, 127, 0, 124); }
;   { const int c0 = hi * 2;
.Lmla_s5_cont:
	s_add_i32 s30, s30, 1
	s_cmpk_lt_u32 s30, 42
	s_cbranch_scc1 .Lmla_stag_loop
	ds_read_b128 v[114:117], v215 offset:24576
	ds_read_b128 v[118:121], v216 offset:24576
	ds_read_b128 v[222:225], v215 offset:28672
	ds_read_b128 v[226:229], v216 offset:28672
	v_exp_f32_e32 v0, v82
	v_exp_f32_e32 v177, v83
	v_exp_f32_e32 v179, v84
	v_exp_f32_e32 v254, v85
	v_add_f32_e32 v219, v0, v177
	v_cvt_pk_fp8_f32 v246, v0, v177
	v_add_f32_e32 v219, v179, v219
	v_add_f32_e32 v219, v254, v219
	v_cvt_pk_fp8_f32 v246, v179, v254 op_sel:[0,0,1]
	s_waitcnt lgkmcnt(2)
	v_mfma_scale_f32_32x32x64_f8f6f4 v[114:129], v[114:121], v[146:153], v[230:245], v194, v193 op_sel_hi:[0,0,0]
	v_exp_f32_e32 v0, v86
	v_exp_f32_e32 v177, v87
	v_exp_f32_e32 v179, v88
	v_exp_f32_e32 v254, v89
	v_add_f32_e32 v219, v0, v219
	v_add_f32_e32 v219, v177, v219
	v_cvt_pk_fp8_f32 v247, v0, v177
	v_add_f32_e32 v219, v179, v219
	v_add_f32_e32 v219, v254, v219
	v_cvt_pk_fp8_f32 v247, v179, v254 op_sel:[0,0,1]
	ds_read_b128 v[82:85], v213 offset:24576
	ds_read_b128 v[86:89], v214 offset:24576
	s_waitcnt lgkmcnt(2)
	v_mfma_scale_f32_32x32x64_f8f6f4 v[98:113], v[222:229], v[146:153], v[230:245], v194, v193 op_sel_hi:[0,0,0]
	ds_read_b128 v[222:225], v213 offset:28672
	ds_read_b128 v[226:229], v214 offset:28672
	v_exp_f32_e32 v0, v90
	v_exp_f32_e32 v177, v91
	v_exp_f32_e32 v179, v92
	v_exp_f32_e32 v254, v93
	v_add_f32_e32 v219, v0, v219
	v_add_f32_e32 v219, v177, v219
	v_cvt_pk_fp8_f32 v248, v0, v177
	v_add_f32_e32 v219, v179, v219
	v_add_f32_e32 v219, v254, v219
	v_cvt_pk_fp8_f32 v248, v179, v254 op_sel:[0,0,1]
	v_exp_f32_e32 v0, v94
	v_exp_f32_e32 v177, v95
	v_exp_f32_e32 v179, v96
	v_exp_f32_e32 v254, v97
	v_add_f32_e32 v219, v0, v219
	v_add_f32_e32 v219, v177, v219
	v_cvt_pk_fp8_f32 v249, v0, v177
	v_add_f32_e32 v219, v179, v219
	v_add_f32_e32 v219, v254, v219
	v_cvt_pk_fp8_f32 v249, v179, v254 op_sel:[0,0,1]
	ds_read_b128 v[90:93], v185 offset:36864
	ds_read_b128 v[94:97], v186 offset:36864
	s_waitcnt lgkmcnt(4)
	v_mfma_scale_f32_32x32x64_f8f6f4 v[114:129], v[82:89], v[138:145], v[114:129], v194, v193 op_sel_hi:[0,0,0]
	v_exp_f32_e32 v0, v66
	v_exp_f32_e32 v177, v67
	v_exp_f32_e32 v179, v68
	v_exp_f32_e32 v254, v69
	v_add_f32_e32 v219, v0, v219
	v_add_f32_e32 v219, v177, v219
	v_cvt_pk_fp8_f32 v250, v0, v177
	v_add_f32_e32 v219, v179, v219
	v_add_f32_e32 v219, v254, v219
	v_cvt_pk_fp8_f32 v250, v179, v254 op_sel:[0,0,1]
	s_waitcnt lgkmcnt(2)
	v_mfma_scale_f32_32x32x64_f8f6f4 v[98:113], v[222:229], v[138:145], v[98:113], v194, v193 op_sel_hi:[0,0,0]
	ds_read_b128 v[222:225], v185 offset:38912
	ds_read_b128 v[226:229], v186 offset:38912
	v_exp_f32_e32 v0, v70
	v_exp_f32_e32 v177, v71
	v_exp_f32_e32 v179, v72
	v_exp_f32_e32 v254, v73
	v_add_f32_e32 v219, v0, v219
	v_add_f32_e32 v219, v177, v219
	v_cvt_pk_fp8_f32 v251, v0, v177
	v_add_f32_e32 v219, v179, v219
	v_add_f32_e32 v219, v254, v219
	v_cvt_pk_fp8_f32 v251, v179, v254 op_sel:[0,0,1]
	v_exp_f32_e32 v0, v74
	v_exp_f32_e32 v177, v75
	v_exp_f32_e32 v179, v76
	v_exp_f32_e32 v254, v77
	v_add_f32_e32 v219, v0, v219
	v_add_f32_e32 v219, v177, v219
	v_cvt_pk_fp8_f32 v252, v0, v177
	v_add_f32_e32 v219, v179, v219
	v_add_f32_e32 v219, v254, v219
	v_cvt_pk_fp8_f32 v252, v179, v254 op_sel:[0,0,1]
	s_waitcnt lgkmcnt(2)
	v_mfma_scale_f32_32x32x64_f8f6f4 v[114:129], v[90:97], v[130:137], v[114:129], v194, v193 op_sel_hi:[0,0,0]
	v_exp_f32_e32 v0, v78
	v_exp_f32_e32 v177, v79
	v_exp_f32_e32 v179, v80
	v_exp_f32_e32 v254, v81
	v_add_f32_e32 v219, v0, v219
	v_add_f32_e32 v219, v177, v219
	v_cvt_pk_fp8_f32 v253, v0, v177
	v_add_f32_e32 v219, v179, v219
	v_add_f32_e32 v219, v254, v219
	v_cvt_pk_fp8_f32 v253, v179, v254 op_sel:[0,0,1]
	ds_read_b128 v[90:93], v185 offset:0
	ds_read_b128 v[94:97], v186 offset:0
	ds_read_b128 v[82:85], v185 offset:2048
	ds_read_b128 v[86:89], v186 offset:2048
	ds_read_b128 v[74:77], v185 offset:4096
	ds_read_b128 v[78:81], v186 offset:4096
	ds_read_b128 v[66:69], v185 offset:6144
	ds_read_b128 v[70:73], v186 offset:6144
	s_waitcnt vmcnt(0)
	ds_write_b128 v210, v[158:161] offset:43008
	ds_write_b128 v211, v[162:165] offset:51200
	s_waitcnt lgkmcnt(10)
	v_mfma_scale_f32_32x32x64_f8f6f4 v[98:113], v[222:229], v[130:137], v[98:113], v194, v193 op_sel_hi:[0,0,0]
	s_waitcnt lgkmcnt(0)
	s_barrier
	global_load_dwordx4 v[158:161], v176, s[18:19]
	global_load_dwordx4 v[162:165], v178, s[16:17]
	v_add_u32_e32 v176, 0x2000, v176
	v_add_u32_e32 v178, 0x20000, v178
	v_mov_b32_e32 v0, v219
	s_nop 1
	v_permlane32_swap_b32_e32 v219, v0
	v_add_f32_e32 v219, v219, v0
	v_fma_f32 v209, v209, v218, v219
	v_max_f32_e32 v177, v114, v115
	v_max3_f32 v177, v177, v116, v117
	v_max3_f32 v177, v177, v118, v119
	v_max3_f32 v177, v177, v120, v121
	v_max3_f32 v177, v177, v122, v123
	v_max3_f32 v177, v177, v124, v125
	v_max3_f32 v177, v177, v126, v127
	v_max3_f32 v177, v177, v128, v129
	s_waitcnt lgkmcnt(6)
	v_mfma_scale_f32_32x32x64_f8f6f4 v[50:65], v[246:253], v[90:97], v[50:65], v194, v194 op_sel_hi:[0,0,0]
	s_waitcnt lgkmcnt(4)
	v_mfma_scale_f32_32x32x64_f8f6f4 v[34:49], v[246:253], v[82:89], v[34:49], v194, v194 op_sel_hi:[0,0,0]
	s_waitcnt lgkmcnt(2)
	v_mfma_scale_f32_32x32x64_f8f6f4 v[18:33], v[246:253], v[74:81], v[18:33], v194, v194 op_sel_hi:[0,0,0]
	s_waitcnt lgkmcnt(0)
	v_mfma_scale_f32_32x32x64_f8f6f4 v[2:17], v[246:253], v[66:73], v[2:17], v194, v194 op_sel_hi:[0,0,0]
	v_max_f32_e32 v0, v98, v99
	v_max3_f32 v0, v0, v100, v101
	v_max3_f32 v0, v0, v102, v103
	v_max3_f32 v0, v0, v104, v105
	v_max3_f32 v0, v0, v106, v107
	v_max3_f32 v0, v0, v108, v109
	v_max3_f32 v0, v0, v110, v111
	v_max3_f32 v0, v0, v112, v113
	v_max_f32_e32 v177, v177, v0
	v_mov_b32_e32 v0, v177
	v_mov_b32_e32 v221, 1.0
	s_nop 0
	v_permlane32_swap_b32_e32 v177, v0
	v_max_f32_e32 v177, v177, v0
	v_cmp_ge_f32_e32 vcc, s90, v177
	s_cmp_eq_u64 vcc, exec
	s_cbranch_scc0 .Lmla_q0_newmax
; __device__ __forceinline__ void finishSM9(f32x16& p0, f32x16& p1, float alpha, float& l_reg, v8i32& p8) {
; #pragma unroll
;   for (int r = 0; r < 16; ++r) { p0[r] = __builtin_amdgcn_exp2f(p0[r]); p1[r] = __builtin_amdgcn_exp2f(p1[r]); }
;   float ps = 0;
; #pragma unroll
;   for (int r = 0; r < 16; ++r) ps += p0[r];
; #pragma unroll
;   for (int r = 0; r < 16; ++r) ps += p1[r];
;   { auto rr = __builtin_amdgcn_permlane32_swap(__float_as_uint(ps), __float_as_uint(ps), false, false);
;     ps = __uint_as_float(rr[0]) + __uint_as_float(rr[1]); }
;   l_reg = l_reg * alpha + ps;
; #pragma unroll
;   for (int g = 0; g < 4; ++g) {
;     int w = __builtin_amdgcn_cvt_pk_fp8_f32(p0[4 * g], p0[4 * g + 1], 0, false); p8[g] = __builtin_amdgcn_cvt_pk_fp8_f32(p0[4 * g + 2], p0[4 * g + 3], w, true);
;     int u = __builtin_amdgcn_cvt_pk_fp8_f32(p1[4 * g], p1[4 * g + 1], 0, false); p8[4 + g] = __builtin_amdgcn_cvt_pk_fp8_f32(p1[4 * g + 2], p1[4 * g + 3], u, true); }
; }
; __device__ __forceinline__ void pv8(f32x16* o, const char* Vt, const v8i32 p8, int r32, int hi) {
;   const int sw = (r32 >> 2) & 3, a0 = r32 * 64 + (((hi * 2) ^ sw) << 4), a1 = r32 * 64 + (((hi * 2 + 1) ^ sw) << 4);
; #pragma unroll
;   for (int d0 = 0; d0 < 4; ++d0) {
;     const v8i32 vf = cat8(*reinterpret_cast<const v4i32*>(Vt + d0 * 2048 + a0), *reinterpret_cast<const v4i32*>(Vt + d0 * 2048 + a1));
;     o[d0] = __builtin_amdgcn_mfma_scale_f32_32x32x64_f8f6f4(p8, vf, o[d0], 0, 0, 0, 127, 0, 127); }
; }
; __device__ __forceinline__ void qkt9(f32x16& p0, f32x16& p1, const char* Kn, const char* Kr, const v8i32* qf, const float init, int r32, int hi) {
; #pragma unroll
;   for (int r = 0; r < 16; ++r) { p0[r] = init; p1[r] = init; }
; #pragma unroll
;   for (int s = 0; s < 2; ++s) { const int c0 = s * 4 + hi * 2;
;     const v8i32 a0 = cat8(*reinterpret_cast<const v4i32*>(Kn + KN8SW(r32, c0)), *reinterpret_cast<const v4i32*>(Kn + KN8SW(r32, c0 + 1)));
;     const v8i32 a1 = cat8(*reinterpret_cast<const v4i32*>(Kn + 4096 + KN8SW(r32, c0)), *reinterpret_cast<const v4i32*>(Kn + 4096 + KN8SW(r32, c0 + 1)));
;     p0 = __builtin_amdgcn_mfma_scale_f32_32x32x64_f8f6f4(a0, qf[s], p0, 0, 0, 0, 127, 0, 124);
;     p1 = __builtin_amdgcn_mfma_scale_f32_32x32x64_f8f6f4(a1, qf[s], p1, 0, 0, 0, 127, 0, 124); }
;   { const int c0 = hi * 2;
.Lmla_q0_cont:
	ds_read_b128 v[82:85], v215 offset:51200
	ds_read_b128 v[86:89], v216 offset:51200
	ds_read_b128 v[222:225], v215 offset:55296
	ds_read_b128 v[226:229], v216 offset:55296
	v_exp_f32_e32 v0, v114
	v_exp_f32_e32 v177, v115
	v_exp_f32_e32 v179, v116
	v_exp_f32_e32 v254, v117
	v_add_f32_e32 v219, v0, v177
	v_cvt_pk_fp8_f32 v246, v0, v177
	v_add_f32_e32 v219, v179, v219
	v_add_f32_e32 v219, v254, v219
	v_cvt_pk_fp8_f32 v246, v179, v254 op_sel:[0,0,1]
	s_waitcnt lgkmcnt(2)
	v_mfma_scale_f32_32x32x64_f8f6f4 v[82:97], v[82:89], v[146:153], v[230:245], v194, v193 op_sel_hi:[0,0,0]
	v_exp_f32_e32 v0, v118
	v_exp_f32_e32 v177, v119
	v_exp_f32_e32 v179, v120
	v_exp_f32_e32 v254, v121
	v_add_f32_e32 v219, v0, v219
	v_add_f32_e32 v219, v177, v219
	v_cvt_pk_fp8_f32 v247, v0, v177
	v_add_f32_e32 v219, v179, v219
	v_add_f32_e32 v219, v254, v219
	v_cvt_pk_fp8_f32 v247, v179, v254 op_sel:[0,0,1]
	ds_read_b128 v[114:117], v213 offset:51200
	ds_read_b128 v[118:121], v214 offset:51200
	s_waitcnt lgkmcnt(2)
	v_mfma_scale_f32_32x32x64_f8f6f4 v[66:81], v[222:229], v[146:153], v[230:245], v194, v193 op_sel_hi:[0,0,0]
	ds_read_b128 v[222:225], v213 offset:55296
	ds_read_b128 v[226:229], v214 offset:55296
	v_exp_f32_e32 v0, v122
	v_exp_f32_e32 v177, v123
	v_exp_f32_e32 v179, v124
	v_exp_f32_e32 v254, v125
	v_add_f32_e32 v219, v0, v219
	v_add_f32_e32 v219, v177, v219
	v_cvt_pk_fp8_f32 v248, v0, v177
	v_add_f32_e32 v219, v179, v219
	v_add_f32_e32 v219, v254, v219
	v_cvt_pk_fp8_f32 v248, v179, v254 op_sel:[0,0,1]
	v_exp_f32_e32 v0, v126
	v_exp_f32_e32 v177, v127
	v_exp_f32_e32 v179, v128
	v_exp_f32_e32 v254, v129
	v_add_f32_e32 v219, v0, v219
	v_add_f32_e32 v219, v177, v219
	v_cvt_pk_fp8_f32 v249, v0, v177
	v_add_f32_e32 v219, v179, v219
	v_add_f32_e32 v219, v254, v219
	v_cvt_pk_fp8_f32 v249, v179, v254 op_sel:[0,0,1]
	ds_read_b128 v[122:125], v185 offset:59392
	ds_read_b128 v[126:129], v186 offset:59392
	s_waitcnt lgkmcnt(4)
	v_mfma_scale_f32_32x32x64_f8f6f4 v[82:97], v[114:121], v[138:145], v[82:97], v194, v193 op_sel_hi:[0,0,0]
	v_exp_f32_e32 v0, v98
	v_exp_f32_e32 v177, v99
	v_exp_f32_e32 v179, v100
	v_exp_f32_e32 v254, v101
	v_add_f32_e32 v219, v0, v219
	v_add_f32_e32 v219, v177, v219
	v_cvt_pk_fp8_f32 v250, v0, v177
	v_add_f32_e32 v219, v179, v219
	v_add_f32_e32 v219, v254, v219
	v_cvt_pk_fp8_f32 v250, v179, v254 op_sel:[0,0,1]
	s_waitcnt lgkmcnt(2)
	v_mfma_scale_f32_32x32x64_f8f6f4 v[66:81], v[222:229], v[138:145], v[66:81], v194, v193 op_sel_hi:[0,0,0]
	ds_read_b128 v[222:225], v185 offset:61440
	ds_read_b128 v[226:229], v186 offset:61440
	v_exp_f32_e32 v0, v102
	v_exp_f32_e32 v177, v103
	v_exp_f32_e32 v179, v104
	v_exp_f32_e32 v254, v105
	v_add_f32_e32 v219, v0, v219
	v_add_f32_e32 v219, v177, v219
	v_cvt_pk_fp8_f32 v251, v0, v177
	v_add_f32_e32 v219, v179, v219
	v_add_f32_e32 v219, v254, v219
	v_cvt_pk_fp8_f32 v251, v179, v254 op_sel:[0,0,1]
	v_exp_f32_e32 v0, v106
	v_exp_f32_e32 v177, v107
	v_exp_f32_e32 v179, v108
	v_exp_f32_e32 v254, v109
	v_add_f32_e32 v219, v0, v219
	v_add_f32_e32 v219, v177, v219
	v_cvt_pk_fp8_f32 v252, v0, v177
	v_add_f32_e32 v219, v179, v219
	v_add_f32_e32 v219, v254, v219
	v_cvt_pk_fp8_f32 v252, v179, v254 op_sel:[0,0,1]
	s_waitcnt lgkmcnt(2)
	v_mfma_scale_f32_32x32x64_f8f6f4 v[82:97], v[122:129], v[130:137], v[82:97], v194, v193 op_sel_hi:[0,0,0]
	v_exp_f32_e32 v0, v110
	v_exp_f32_e32 v177, v111
	v_exp_f32_e32 v179, v112
	v_exp_f32_e32 v254, v113
	v_add_f32_e32 v219, v0, v219
	v_add_f32_e32 v219, v177, v219
	v_cvt_pk_fp8_f32 v253, v0, v177
	v_add_f32_e32 v219, v179, v219
	v_add_f32_e32 v219, v254, v219
	v_cvt_pk_fp8_f32 v253, v179, v254 op_sel:[0,0,1]
	ds_read_b128 v[122:125], v185 offset:8192
	ds_read_b128 v[126:129], v186 offset:8192
	ds_read_b128 v[114:117], v185 offset:10240
	ds_read_b128 v[118:121], v186 offset:10240
	ds_read_b128 v[106:109], v185 offset:12288
	ds_read_b128 v[110:113], v186 offset:12288
	ds_read_b128 v[98:101], v185 offset:14336
	ds_read_b128 v[102:105], v186 offset:14336
	s_waitcnt vmcnt(0)
	ds_write_b128 v210, v[158:161]
	ds_write_b128 v211, v[162:165] offset:16384
	s_waitcnt lgkmcnt(10)
	v_mfma_scale_f32_32x32x64_f8f6f4 v[66:81], v[222:229], v[130:137], v[66:81], v194, v193 op_sel_hi:[0,0,0]
	s_waitcnt lgkmcnt(0)
	s_barrier
	v_mov_b32_e32 v0, v219
	s_nop 1
	v_permlane32_swap_b32_e32 v219, v0
	v_add_f32_e32 v219, v219, v0
	v_fma_f32 v209, v209, v221, v219
	v_max_f32_e32 v177, v82, v83
	v_max3_f32 v177, v177, v84, v85
	v_max3_f32 v177, v177, v86, v87
	v_max3_f32 v177, v177, v88, v89
	v_max3_f32 v177, v177, v90, v91
	v_max3_f32 v177, v177, v92, v93
	v_max3_f32 v177, v177, v94, v95
	v_max3_f32 v177, v177, v96, v97
	s_waitcnt lgkmcnt(6)
	v_mfma_scale_f32_32x32x64_f8f6f4 v[50:65], v[246:253], v[122:129], v[50:65], v194, v194 op_sel_hi:[0,0,0]
	s_waitcnt lgkmcnt(4)
	v_mfma_scale_f32_32x32x64_f8f6f4 v[34:49], v[246:253], v[114:121], v[34:49], v194, v194 op_sel_hi:[0,0,0]
	s_waitcnt lgkmcnt(2)
	v_mfma_scale_f32_32x32x64_f8f6f4 v[18:33], v[246:253], v[106:113], v[18:33], v194, v194 op_sel_hi:[0,0,0]
	s_waitcnt lgkmcnt(0)
	v_mfma_scale_f32_32x32x64_f8f6f4 v[2:17], v[246:253], v[98:105], v[2:17], v194, v194 op_sel_hi:[0,0,0]
	v_max_f32_e32 v0, v66, v67
	v_max3_f32 v0, v0, v68, v69
	v_max3_f32 v0, v0, v70, v71
	v_max3_f32 v0, v0, v72, v73
	v_max3_f32 v0, v0, v74, v75
	v_max3_f32 v0, v0, v76, v77
	v_max3_f32 v0, v0, v78, v79
	v_max3_f32 v0, v0, v80, v81
	v_max_f32_e32 v177, v177, v0
	v_mov_b32_e32 v0, v177
	v_mov_b32_e32 v218, 1.0
	s_nop 0
	v_permlane32_swap_b32_e32 v177, v0
	v_max_f32_e32 v177, v177, v0
	v_cmp_ge_f32_e32 vcc, s90, v177
	s_cmp_eq_u64 vcc, exec
	s_cbranch_scc0 .Lmla_q1_newmax
